# v03: transpose batching + SSM U prefetch + removed accumulator zeroing (SrcC=0) in attention/SSM loops
# speedup vs baseline: 1.0039x; 1.0039x over previous
.LBB0_375:
	s_or_b64 exec, exec, s[14:15]
	s_add_i32 s14, s17, 1
	s_ashr_i32 s3, s2, 31
	s_bitcmp1_b32 s17, 0
	v_lshl_add_u64 v[2:3], s[2:3], 1, v[130:131]
	s_cselect_b32 s2, 0x2e00, 0
	s_add_i32 s2, s18, s2
	v_add3_u32 v0, s2, v153, v154
	global_load_dwordx4 v[94:97], v[2:3], off
	ds_read_b128 v[132:135], v0
	ds_read_b128 v[136:139], v0 offset:32
	ds_read_b128 v[140:143], v0 offset:64
	ds_read_b128 v[160:163], v0 offset:96
	ds_read_b128 v[164:167], v0 offset:128
	ds_read_b128 v[168:171], v0 offset:160
	v_add3_u32 v0, s2, v102, v155
	v_add_u32_e32 v2, 0x1800, v0
	v_add_u32_e32 v0, 0x2000, v0
	ds_read2_b64 v[172:175], v2 offset0:64 offset1:66
	ds_read2_b64 v[176:179], v2 offset0:68 offset1:70
	ds_read2_b64 v[180:183], v0 offset0:128 offset1:130
	ds_read2_b64 v[184:187], v0 offset0:132 offset1:134
	s_bitcmp1_b32 s14, 0
	s_cselect_b32 s2, 0x2e00, 0
	s_waitcnt lgkmcnt(9)
	v_mfma_f32_32x32x16_bf16 v[48:63], v[132:135], v[70:73], 0
	s_add_i32 s15, s18, s2
	s_waitcnt lgkmcnt(8)
	v_mfma_f32_32x32x16_bf16 v[48:63], v[136:139], v[74:77], v[48:63]
	s_waitcnt lgkmcnt(7)
	v_mfma_f32_32x32x16_bf16 v[48:63], v[140:143], v[78:81], v[48:63]
	s_waitcnt lgkmcnt(6)
	v_mfma_f32_32x32x16_bf16 v[48:63], v[160:163], v[82:85], v[48:63]
	s_waitcnt lgkmcnt(5)
	v_mfma_f32_32x32x16_bf16 v[48:63], v[164:167], v[86:89], v[48:63]
	s_waitcnt lgkmcnt(4)
	v_mfma_f32_32x32x16_bf16 v[48:63], v[168:171], v[90:93], v[48:63]
	s_nop 11
	v_max_f32_e32 v0, v49, v49
	v_max_f32_e32 v2, v48, v48
	v_max_f32_e32 v0, v2, v0
	v_max3_f32 v0, v0, v50, v51
	v_max3_f32 v0, v0, v52, v53
	v_max3_f32 v0, v0, v54, v55
	v_max3_f32 v0, v0, v56, v57
	v_max3_f32 v0, v0, v58, v59
	v_max3_f32 v0, v0, v60, v61
	v_max3_f32 v0, v0, v62, v63
	ds_bpermute_b32 v2, v103, v0
	s_waitcnt lgkmcnt(0)
	v_max3_f32 v115, v117, v0, v2
	v_sub_f32_e32 v0, v117, v115
	v_sub_f32_e32 v2, v48, v115
	v_sub_f32_e32 v3, v49, v115
	v_sub_f32_e32 v4, v50, v115
	v_sub_f32_e32 v5, v51, v115
	v_sub_f32_e32 v6, v52, v115
	v_sub_f32_e32 v7, v53, v115
	v_sub_f32_e32 v8, v54, v115
	v_sub_f32_e32 v9, v55, v115
	v_exp_f32_e32 v2, v2
	v_exp_f32_e32 v3, v3
	v_exp_f32_e32 v4, v4
	v_exp_f32_e32 v5, v5
	v_exp_f32_e32 v6, v6
	v_exp_f32_e32 v7, v7
	v_exp_f32_e32 v8, v8
	v_exp_f32_e32 v9, v9
	v_exp_f32_e32 v0, v0
	v_cvt_pk_bf16_f32 v48, v2, v3
	v_cvt_pk_bf16_f32 v49, v4, v5
	v_cvt_pk_bf16_f32 v50, v6, v7
	v_pk_mul_f32 v[46:47], v[46:47], v[0:1] op_sel_hi:[1,0]
	v_pk_mul_f32 v[44:45], v[44:45], v[0:1] op_sel_hi:[1,0]
	v_pk_mul_f32 v[42:43], v[42:43], v[0:1] op_sel_hi:[1,0]
	v_pk_mul_f32 v[40:41], v[40:41], v[0:1] op_sel_hi:[1,0]
	v_pk_mul_f32 v[38:39], v[38:39], v[0:1] op_sel_hi:[1,0]
	v_pk_mul_f32 v[36:37], v[36:37], v[0:1] op_sel_hi:[1,0]
	v_pk_mul_f32 v[34:35], v[34:35], v[0:1] op_sel_hi:[1,0]
	v_pk_mul_f32 v[32:33], v[32:33], v[0:1] op_sel_hi:[1,0]
	v_pk_mul_f32 v[30:31], v[30:31], v[0:1] op_sel_hi:[1,0]
	v_cvt_pk_bf16_f32 v51, v8, v9
	v_pk_mul_f32 v[28:29], v[28:29], v[0:1] op_sel_hi:[1,0]
	v_pk_mul_f32 v[26:27], v[26:27], v[0:1] op_sel_hi:[1,0]
	v_pk_mul_f32 v[24:25], v[24:25], v[0:1] op_sel_hi:[1,0]
	v_pk_mul_f32 v[22:23], v[22:23], v[0:1] op_sel_hi:[1,0]
	v_pk_mul_f32 v[20:21], v[20:21], v[0:1] op_sel_hi:[1,0]
	v_pk_mul_f32 v[18:19], v[18:19], v[0:1] op_sel_hi:[1,0]
	v_pk_mul_f32 v[16:17], v[16:17], v[0:1] op_sel_hi:[1,0]
	v_mfma_f32_32x32x16_bf16 v[32:47], v[172:175], v[48:51], v[32:47]
	v_sub_f32_e32 v10, v56, v115
	v_sub_f32_e32 v11, v57, v115
	v_sub_f32_e32 v12, v58, v115
	v_sub_f32_e32 v13, v59, v115
	v_sub_f32_e32 v14, v60, v115
	v_sub_f32_e32 v15, v61, v115
	v_sub_f32_e32 v52, v62, v115
	v_mfma_f32_32x32x16_bf16 v[16:31], v[180:183], v[48:51], v[16:31]
	v_sub_f32_e32 v49, v63, v115
	v_exp_f32_e32 v10, v10
	v_exp_f32_e32 v11, v11
	v_exp_f32_e32 v12, v12
	v_exp_f32_e32 v13, v13
	v_exp_f32_e32 v14, v14
	v_exp_f32_e32 v15, v15
	v_exp_f32_e32 v48, v52
	v_exp_f32_e32 v49, v49
	v_cvt_pk_bf16_f32 v50, v10, v11
	v_cvt_pk_bf16_f32 v51, v12, v13
	v_cvt_pk_bf16_f32 v52, v14, v15
	v_cvt_pk_bf16_f32 v53, v48, v49
	s_nop 1
	v_mfma_f32_32x32x16_bf16 v[32:47], v[176:179], v[50:53], v[32:47]
	v_mfma_f32_32x32x16_bf16 v[16:31], v[184:187], v[50:53], v[16:31]
	v_add3_u32 v50, s15, v148, v149
	s_waitcnt vmcnt(1)
	ds_write_b128 v50, v[98:101]
	s_and_saveexec_b64 s[2:3], s[0:1]
	v_add3_u32 v50, s15, v150, v156
	ds_write_b128 v50, v[66:69]
	s_or_b64 exec, exec, s[2:3]
	v_add_f32_e32 v2, 0, v2
	v_add_f32_e32 v2, v3, v2
	v_add_f32_e32 v2, v4, v2
	v_add_f32_e32 v2, v5, v2
	v_add_f32_e32 v2, v6, v2
	v_add_f32_e32 v2, v7, v2
	v_add_f32_e32 v2, v8, v2
	v_add_f32_e32 v2, v9, v2
	v_add_f32_e32 v2, v10, v2
	v_add_f32_e32 v2, v11, v2
	v_add_f32_e32 v2, v12, v2
	v_add_f32_e32 v2, v13, v2
	v_add_f32_e32 v2, v14, v2
	v_add_f32_e32 v2, v15, v2
	v_add_f32_e32 v2, v48, v2
	v_add_f32_e32 v98, v49, v2
	s_add_i32 s16, s16, 32
	v_fmac_f32_e32 v98, v113, v0
	v_add3_u32 v0, s15, v151, v152
	s_cmp_eq_u32 s14, 39
	s_waitcnt vmcnt(0)
	ds_write_b128 v0, v[94:97] offset:6656
	s_waitcnt lgkmcnt(0)
	s_barrier
	s_cbranch_scc1 .LBB0_379
	v_mov_b32_e32 v113, v98
	v_mov_b32_e32 v117, v115
	s_mov_b32 s17, s14
	s_branch .LBB0_373

.LBB0_391:
	s_or_b64 exec, exec, s[2:3]
	s_bitcmp1_b32 s7, 0
	s_cselect_b32 s3, 0, 0x2e00
	s_cselect_b32 s2, 0x2e00, 0
	s_add_i32 s3, s18, s3
	v_add3_u32 v0, s3, v153, v154
	global_load_dwordx4 v[92:95], v[126:127], off
	ds_read_b128 v[128:131], v0
	ds_read_b128 v[132:135], v0 offset:32
	ds_read_b128 v[136:139], v0 offset:64
	ds_read_b128 v[160:163], v0 offset:96
	ds_read_b128 v[164:167], v0 offset:128
	ds_read_b128 v[168:171], v0 offset:160
	v_add3_u32 v0, s3, v102, v155
	v_add_u32_e32 v2, 0x1800, v0
	v_add_u32_e32 v0, 0x2000, v0
	ds_read2_b64 v[172:175], v2 offset0:64 offset1:66
	ds_read2_b64 v[176:179], v2 offset0:68 offset1:70
	ds_read2_b64 v[180:183], v0 offset0:128 offset1:130
	ds_read2_b64 v[184:187], v0 offset0:132 offset1:134
	s_add_i32 s8, s18, s2
	s_waitcnt lgkmcnt(9)
	v_mfma_f32_32x32x16_bf16 v[48:63], v[128:131], v[68:71], 0
	s_waitcnt lgkmcnt(8)
	v_mfma_f32_32x32x16_bf16 v[48:63], v[132:135], v[72:75], v[48:63]
	s_waitcnt lgkmcnt(7)
	v_mfma_f32_32x32x16_bf16 v[48:63], v[136:139], v[76:79], v[48:63]
	s_waitcnt lgkmcnt(6)
	v_mfma_f32_32x32x16_bf16 v[48:63], v[160:163], v[80:83], v[48:63]
	s_waitcnt lgkmcnt(5)
	v_mfma_f32_32x32x16_bf16 v[48:63], v[164:167], v[84:87], v[48:63]
	s_waitcnt lgkmcnt(4)
	v_mfma_f32_32x32x16_bf16 v[48:63], v[168:171], v[88:91], v[48:63]
	s_nop 11
	v_max_f32_e32 v0, v49, v49
	v_max_f32_e32 v2, v48, v48
	v_max_f32_e32 v0, v2, v0
	v_max3_f32 v0, v0, v50, v51
	v_max3_f32 v0, v0, v52, v53
	v_max3_f32 v0, v0, v54, v55
	v_max3_f32 v0, v0, v56, v57
	v_max3_f32 v0, v0, v58, v59
	v_max3_f32 v0, v0, v60, v61
	v_max3_f32 v0, v0, v62, v63
	ds_bpermute_b32 v2, v103, v0
	s_waitcnt lgkmcnt(0)
	v_max3_f32 v119, v121, v0, v2
	v_sub_f32_e32 v0, v121, v119
	v_sub_f32_e32 v2, v48, v119
	v_sub_f32_e32 v3, v49, v119
	v_sub_f32_e32 v4, v50, v119
	v_sub_f32_e32 v5, v51, v119
	v_sub_f32_e32 v6, v52, v119
	v_sub_f32_e32 v7, v53, v119
	v_sub_f32_e32 v8, v54, v119
	v_sub_f32_e32 v9, v55, v119
	v_exp_f32_e32 v2, v2
	v_exp_f32_e32 v3, v3
	v_exp_f32_e32 v4, v4
	v_exp_f32_e32 v5, v5
	v_exp_f32_e32 v6, v6
	v_exp_f32_e32 v7, v7
	v_exp_f32_e32 v8, v8
	v_exp_f32_e32 v9, v9
	v_exp_f32_e32 v0, v0
	v_cvt_pk_bf16_f32 v48, v2, v3
	v_cvt_pk_bf16_f32 v49, v4, v5
	v_cvt_pk_bf16_f32 v50, v6, v7
	v_pk_mul_f32 v[46:47], v[46:47], v[0:1] op_sel_hi:[1,0]
	v_pk_mul_f32 v[44:45], v[44:45], v[0:1] op_sel_hi:[1,0]
	v_pk_mul_f32 v[42:43], v[42:43], v[0:1] op_sel_hi:[1,0]
	v_pk_mul_f32 v[40:41], v[40:41], v[0:1] op_sel_hi:[1,0]
	v_pk_mul_f32 v[38:39], v[38:39], v[0:1] op_sel_hi:[1,0]
	v_pk_mul_f32 v[36:37], v[36:37], v[0:1] op_sel_hi:[1,0]
	v_pk_mul_f32 v[34:35], v[34:35], v[0:1] op_sel_hi:[1,0]
	v_pk_mul_f32 v[32:33], v[32:33], v[0:1] op_sel_hi:[1,0]
	v_pk_mul_f32 v[30:31], v[30:31], v[0:1] op_sel_hi:[1,0]
	v_cvt_pk_bf16_f32 v51, v8, v9
	v_pk_mul_f32 v[28:29], v[28:29], v[0:1] op_sel_hi:[1,0]
	v_pk_mul_f32 v[26:27], v[26:27], v[0:1] op_sel_hi:[1,0]
	v_pk_mul_f32 v[24:25], v[24:25], v[0:1] op_sel_hi:[1,0]
	v_pk_mul_f32 v[22:23], v[22:23], v[0:1] op_sel_hi:[1,0]
	v_pk_mul_f32 v[20:21], v[20:21], v[0:1] op_sel_hi:[1,0]
	v_pk_mul_f32 v[18:19], v[18:19], v[0:1] op_sel_hi:[1,0]
	v_pk_mul_f32 v[16:17], v[16:17], v[0:1] op_sel_hi:[1,0]
	v_mfma_f32_32x32x16_bf16 v[32:47], v[172:175], v[48:51], v[32:47]
	v_sub_f32_e32 v10, v56, v119
	v_sub_f32_e32 v11, v57, v119
	v_sub_f32_e32 v12, v58, v119
	v_sub_f32_e32 v13, v59, v119
	v_sub_f32_e32 v14, v60, v119
	v_sub_f32_e32 v15, v61, v119
	v_sub_f32_e32 v52, v62, v119
	v_mfma_f32_32x32x16_bf16 v[16:31], v[180:183], v[48:51], v[16:31]
	v_sub_f32_e32 v49, v63, v119
	v_exp_f32_e32 v10, v10
	v_exp_f32_e32 v11, v11
	v_exp_f32_e32 v12, v12
	v_exp_f32_e32 v13, v13
	v_exp_f32_e32 v14, v14
	v_exp_f32_e32 v15, v15
	v_exp_f32_e32 v48, v52
	v_exp_f32_e32 v49, v49
	v_cvt_pk_bf16_f32 v50, v10, v11
	v_cvt_pk_bf16_f32 v51, v12, v13
	v_cvt_pk_bf16_f32 v52, v14, v15
	v_cvt_pk_bf16_f32 v53, v48, v49
	s_nop 1
	v_mfma_f32_32x32x16_bf16 v[32:47], v[176:179], v[50:53], v[32:47]
	v_mfma_f32_32x32x16_bf16 v[16:31], v[184:187], v[50:53], v[16:31]
	v_add3_u32 v50, s8, v148, v149
	s_waitcnt vmcnt(1)
	ds_write_b128 v50, v[96:99]
	s_and_saveexec_b64 s[2:3], s[0:1]
	v_add3_u32 v50, s8, v150, v156
	ds_write_b128 v50, v[64:67]
	s_or_b64 exec, exec, s[2:3]
	v_add_f32_e32 v2, 0, v2
	v_add_f32_e32 v2, v3, v2
	v_add_f32_e32 v2, v4, v2
	v_add_f32_e32 v2, v5, v2
	v_add_f32_e32 v2, v6, v2
	v_add_f32_e32 v2, v7, v2
	v_add_f32_e32 v2, v8, v2
	v_add_f32_e32 v2, v9, v2
	v_add_f32_e32 v2, v10, v2
	v_add_f32_e32 v2, v11, v2
	v_add_f32_e32 v2, v12, v2
	v_add_f32_e32 v2, v13, v2
	v_add_f32_e32 v2, v14, v2
	v_add_f32_e32 v2, v15, v2
	v_add_f32_e32 v2, v48, v2
	v_add_f32_e32 v96, v49, v2
	s_add_i32 s7, s7, 1
	v_fmac_f32_e32 v96, v117, v0
	v_add3_u32 v0, s8, v151, v152
	v_add_u32_e32 v113, 32, v113
	v_lshl_add_u64 v[126:127], v[126:127], 0, 64
	s_cmp_eq_u32 s7, 8
	v_add_u32_e32 v115, 32, v115
	s_waitcnt vmcnt(0)
	ds_write_b128 v0, v[92:95] offset:6656
	s_waitcnt lgkmcnt(0)
	s_barrier
	s_cbranch_scc0 .LBB0_389
	v_add3_u32 v0, s8, v153, v154
	ds_read_b128 v[122:125], v0
	ds_read_b128 v[126:129], v0 offset:32
	ds_read_b128 v[130:133], v0 offset:64
	ds_read_b128 v[134:137], v0 offset:96
	ds_read_b128 v[138:141], v0 offset:128
	ds_read_b128 v[160:163], v0 offset:160
	v_add3_u32 v0, s8, v102, v155
	v_add_u32_e32 v2, 0x1800, v0
	v_add_u32_e32 v0, 0x2000, v0
	v_mov_b32_e32 v14, v1
	v_mov_b32_e32 v15, v1
	ds_read2_b64 v[164:167], v2 offset0:64 offset1:66
	ds_read2_b64 v[64:67], v2 offset0:68 offset1:70
	ds_read2_b64 v[168:171], v0 offset0:128 offset1:130
	ds_read2_b64 v[92:95], v0 offset0:132 offset1:134
	v_mov_b32_e32 v0, v1
	v_mov_b32_e32 v2, v1
	v_mov_b32_e32 v3, v1
	v_mov_b32_e32 v4, v1
	v_mov_b32_e32 v5, v1
	v_mov_b32_e32 v6, v1
	v_mov_b32_e32 v7, v1
	v_mov_b32_e32 v8, v1
	v_mov_b32_e32 v9, v1
	v_mov_b32_e32 v10, v1
	v_mov_b32_e32 v11, v1
	v_mov_b32_e32 v12, v1
	v_mov_b32_e32 v13, v1
	v_mov_b64_e32 v[62:63], v[14:15]
	v_mov_b64_e32 v[60:61], v[12:13]
	v_mov_b64_e32 v[58:59], v[10:11]
	v_mov_b64_e32 v[56:57], v[8:9]
	v_mov_b64_e32 v[54:55], v[6:7]
	v_mov_b64_e32 v[52:53], v[4:5]
	v_mov_b64_e32 v[50:51], v[2:3]
	v_mov_b64_e32 v[48:49], v[0:1]
	s_ashr_i32 s7, s6, 31
	v_mov_b32_e32 v121, v1
	s_waitcnt lgkmcnt(9)
	v_mfma_f32_32x32x16_bf16 v[48:63], v[122:125], v[68:71], v[48:63]
	s_waitcnt lgkmcnt(0)
	s_barrier
	s_add_i32 s5, s5, s26
	v_mfma_f32_32x32x16_bf16 v[48:63], v[126:129], v[72:75], v[48:63]
	v_mfma_f32_32x32x16_bf16 v[48:63], v[130:133], v[76:79], v[48:63]
	v_mfma_f32_32x32x16_bf16 v[48:63], v[134:137], v[80:83], v[48:63]
	v_mfma_f32_32x32x16_bf16 v[48:63], v[138:141], v[84:87], v[48:63]
	v_mfma_f32_32x32x16_bf16 v[48:63], v[160:163], v[88:91], v[48:63]
	s_nop 11
	v_max_f32_e32 v0, v49, v49
	v_max_f32_e32 v2, v48, v48
	v_max_f32_e32 v0, v2, v0
	v_max3_f32 v0, v0, v50, v51
	v_max3_f32 v0, v0, v52, v53
	v_max3_f32 v0, v0, v54, v55
	v_max3_f32 v0, v0, v56, v57
	v_max3_f32 v0, v0, v58, v59
	v_max3_f32 v0, v0, v60, v61
	v_max3_f32 v0, v0, v62, v63
	ds_bpermute_b32 v2, v103, v0
	s_waitcnt lgkmcnt(0)
	v_max3_f32 v6, v119, v0, v2
	v_sub_f32_e32 v2, v48, v6
	v_sub_f32_e32 v3, v49, v6
	v_exp_f32_e32 v2, v2
	v_sub_f32_e32 v4, v50, v6
	v_exp_f32_e32 v3, v3
	v_sub_f32_e32 v5, v51, v6
	v_exp_f32_e32 v4, v4
	v_sub_f32_e32 v7, v52, v6
	v_exp_f32_e32 v5, v5
	v_sub_f32_e32 v8, v53, v6
	v_exp_f32_e32 v7, v7
	v_add_f32_e32 v49, 0, v2
	v_sub_f32_e32 v9, v54, v6
	v_exp_f32_e32 v8, v8
	v_add_f32_e32 v49, v3, v49
	v_sub_f32_e32 v10, v55, v6
	v_exp_f32_e32 v9, v9
	v_add_f32_e32 v49, v4, v49
	v_sub_f32_e32 v0, v119, v6
	v_sub_f32_e32 v11, v56, v6
	v_exp_f32_e32 v10, v10
	v_add_f32_e32 v49, v5, v49
	v_sub_f32_e32 v12, v57, v6
	v_exp_f32_e32 v11, v11
	v_add_f32_e32 v49, v7, v49
	v_exp_f32_e32 v0, v0
	v_sub_f32_e32 v13, v58, v6
	v_exp_f32_e32 v12, v12
	v_add_f32_e32 v49, v8, v49
	v_sub_f32_e32 v14, v59, v6
	v_exp_f32_e32 v13, v13
	v_add_f32_e32 v49, v9, v49
	v_sub_f32_e32 v15, v60, v6
	v_exp_f32_e32 v14, v14
	v_add_f32_e32 v49, v10, v49
	v_sub_f32_e32 v48, v61, v6
	v_exp_f32_e32 v15, v15
	v_add_f32_e32 v49, v11, v49
	v_pk_mul_f32 v[46:47], v[46:47], v[0:1] op_sel_hi:[1,0]
	v_pk_mul_f32 v[44:45], v[44:45], v[0:1] op_sel_hi:[1,0]
	v_pk_mul_f32 v[42:43], v[42:43], v[0:1] op_sel_hi:[1,0]
	v_pk_mul_f32 v[40:41], v[40:41], v[0:1] op_sel_hi:[1,0]
	v_pk_mul_f32 v[38:39], v[38:39], v[0:1] op_sel_hi:[1,0]
	v_pk_mul_f32 v[36:37], v[36:37], v[0:1] op_sel_hi:[1,0]
	v_pk_mul_f32 v[34:35], v[34:35], v[0:1] op_sel_hi:[1,0]
	v_pk_mul_f32 v[32:33], v[32:33], v[0:1] op_sel_hi:[1,0]
	v_pk_mul_f32 v[30:31], v[30:31], v[0:1] op_sel_hi:[1,0]
	v_cvt_pk_bf16_f32 v2, v2, v3
	v_cvt_pk_bf16_f32 v3, v4, v5
	v_cvt_pk_bf16_f32 v4, v7, v8
	v_cvt_pk_bf16_f32 v5, v9, v10
	v_pk_mul_f32 v[28:29], v[28:29], v[0:1] op_sel_hi:[1,0]
	v_pk_mul_f32 v[26:27], v[26:27], v[0:1] op_sel_hi:[1,0]
	v_pk_mul_f32 v[24:25], v[24:25], v[0:1] op_sel_hi:[1,0]
	v_pk_mul_f32 v[22:23], v[22:23], v[0:1] op_sel_hi:[1,0]
	v_pk_mul_f32 v[20:21], v[20:21], v[0:1] op_sel_hi:[1,0]
	v_pk_mul_f32 v[18:19], v[18:19], v[0:1] op_sel_hi:[1,0]
	v_pk_mul_f32 v[16:17], v[16:17], v[0:1] op_sel_hi:[1,0]
	v_exp_f32_e32 v48, v48
	v_add_f32_e32 v49, v12, v49
	v_sub_f32_e32 v50, v62, v6
	v_mfma_f32_32x32x16_bf16 v[32:47], v[164:167], v[2:5], v[32:47]
	v_add_f32_e32 v49, v13, v49
	v_exp_f32_e32 v7, v50
	v_add_f32_e32 v49, v14, v49
	v_add_f32_e32 v49, v15, v49
	v_add_f32_e32 v49, v48, v49
	v_mfma_f32_32x32x16_bf16 v[16:31], v[168:171], v[2:5], v[16:31]
	v_sub_f32_e32 v2, v63, v6
	v_exp_f32_e32 v6, v2
	v_cvt_pk_bf16_f32 v2, v11, v12
	v_cvt_pk_bf16_f32 v3, v13, v14
	v_cvt_pk_bf16_f32 v4, v15, v48
	v_cvt_pk_bf16_f32 v5, v7, v6
	v_add_f32_e32 v7, v7, v49
	v_add_f32_e32 v6, v6, v7
	v_fmac_f32_e32 v6, v96, v0
	ds_bpermute_b32 v0, v103, v6
	v_mfma_f32_32x32x16_bf16 v[32:47], v[64:67], v[2:5], v[32:47]
	s_waitcnt lgkmcnt(0)
	v_add_f32_e32 v0, v6, v0
	v_mfma_f32_32x32x16_bf16 v[16:31], v[92:95], v[2:5], v[16:31]
	v_div_scale_f32 v2, s[2:3], v0, v0, 1.0
	v_rcp_f32_e32 v3, v2
	v_readlane_b32 s2, v253, 6
	v_readlane_b32 s3, v253, 7
	v_fma_f32 v4, -v2, v3, 1.0
	v_fmac_f32_e32 v3, v4, v3
	v_div_scale_f32 v4, vcc, 1.0, v0, 1.0
	v_mul_f32_e32 v5, v4, v3
	v_fma_f32 v6, -v2, v5, v4
	v_fmac_f32_e32 v5, v6, v3
	v_fma_f32 v2, -v2, v5, v4
	v_div_fmas_f32 v2, v2, v3, v5
	v_div_fixup_f32 v0, v2, v0, 1.0
	v_lshl_add_u64 v[2:3], s[6:7], 0, v[108:109]
	v_lshlrev_b64 v[2:3], 10, v[2:3]
	v_lshl_add_u64 v[2:3], s[2:3], 0, v[2:3]
	s_lshl_b32 s2, s12, 1
	s_mov_b32 s3, s4
	v_lshl_add_u64 v[2:3], v[2:3], 0, s[2:3]
	v_pk_mul_f32 v[4:5], v[32:33], v[0:1] op_sel_hi:[1,0]
	v_pk_mul_f32 v[6:7], v[34:35], v[0:1] op_sel_hi:[1,0]
	v_lshl_add_u64 v[2:3], v[2:3], 0, v[120:121]
	v_cvt_pk_bf16_f32 v4, v4, v5
	v_cvt_pk_bf16_f32 v5, v6, v7
	global_store_dwordx2 v[2:3], v[4:5], off
	v_pk_mul_f32 v[4:5], v[16:17], v[0:1] op_sel_hi:[1,0]
	v_pk_mul_f32 v[6:7], v[18:19], v[0:1] op_sel_hi:[1,0]
	v_cvt_pk_bf16_f32 v4, v4, v5
	v_cvt_pk_bf16_f32 v5, v6, v7
	global_store_dwordx2 v[2:3], v[4:5], off offset:64
	v_pk_mul_f32 v[4:5], v[36:37], v[0:1] op_sel_hi:[1,0]
	v_pk_mul_f32 v[6:7], v[38:39], v[0:1] op_sel_hi:[1,0]
	v_cvt_pk_bf16_f32 v4, v4, v5
	v_cvt_pk_bf16_f32 v5, v6, v7
	global_store_dwordx2 v[2:3], v[4:5], off offset:16
	v_pk_mul_f32 v[4:5], v[20:21], v[0:1] op_sel_hi:[1,0]
	v_pk_mul_f32 v[6:7], v[22:23], v[0:1] op_sel_hi:[1,0]
	v_cvt_pk_bf16_f32 v4, v4, v5
	v_cvt_pk_bf16_f32 v5, v6, v7
	global_store_dwordx2 v[2:3], v[4:5], off offset:80
	v_pk_mul_f32 v[4:5], v[40:41], v[0:1] op_sel_hi:[1,0]
	v_pk_mul_f32 v[6:7], v[42:43], v[0:1] op_sel_hi:[1,0]
	v_cvt_pk_bf16_f32 v4, v4, v5
	v_cvt_pk_bf16_f32 v5, v6, v7
	global_store_dwordx2 v[2:3], v[4:5], off offset:32
	v_pk_mul_f32 v[4:5], v[24:25], v[0:1] op_sel_hi:[1,0]
	v_pk_mul_f32 v[6:7], v[26:27], v[0:1] op_sel_hi:[1,0]
	v_cvt_pk_bf16_f32 v4, v4, v5
	v_cvt_pk_bf16_f32 v5, v6, v7
	global_store_dwordx2 v[2:3], v[4:5], off offset:96
	v_pk_mul_f32 v[4:5], v[44:45], v[0:1] op_sel_hi:[1,0]
	v_pk_mul_f32 v[6:7], v[46:47], v[0:1] op_sel_hi:[1,0]
	v_cvt_pk_bf16_f32 v4, v4, v5
	v_cvt_pk_bf16_f32 v5, v6, v7
	global_store_dwordx2 v[2:3], v[4:5], off offset:48
	v_pk_mul_f32 v[4:5], v[28:29], v[0:1] op_sel_hi:[1,0]
	v_pk_mul_f32 v[6:7], v[30:31], v[0:1] op_sel_hi:[1,0]
	v_cvt_pk_bf16_f32 v4, v4, v5
	v_cvt_pk_bf16_f32 v5, v6, v7
	s_cmpk_gt_i32 s5, 0xff
	global_store_dwordx2 v[2:3], v[4:5], off offset:112
	s_cbranch_scc0 .LBB0_384

.LBB0_515:
	s_lshl_b64 s[2:3], s[2:3], 12
	v_lshl_add_u64 v[2:3], v[102:103], 0, s[2:3]
	global_load_dwordx4 v[68:71], v[2:3], off
	global_load_dwordx4 v[72:75], v[2:3], off offset:1024
	global_load_dwordx4 v[76:79], v[2:3], off offset:2048
	global_load_dwordx4 v[80:83], v[2:3], off offset:3072
	v_lshl_add_u64 v[2:3], v[104:105], 0, s[2:3]
	global_load_dwordx4 v[84:87], v[2:3], off
	global_load_dwordx4 v[88:91], v[2:3], off offset:64
	global_load_dwordx4 v[92:95], v[2:3], off offset:128
	global_load_dwordx4 v[96:99], v[2:3], off offset:192
	s_mul_i32 s2, s52, 0xc00000
	s_mul_hi_u32 s3, s73, 0xc00000
	s_add_i32 s3, s3, s2
	s_mul_i32 s2, s73, 0xc00000
	v_readlane_b32 s6, v251, 36
	v_readlane_b32 s7, v251, 37
	s_add_u32 s5, s6, s2
	s_addc_u32 s6, s7, s3
	s_lshl_b32 s2, s53, 5
	s_mov_b32 s3, s4
	v_lshl_add_u64 v[112:113], v[106:107], 0, s[2:3]
	s_add_u32 s2, s5, s2
	s_addc_u32 s3, s6, 0
	v_lshl_add_u64 v[114:115], s[2:3], 0, v[0:1]
	v_add_u32_e32 v140, s39, v124
	v_add_u32_e32 v141, s39, v128
	v_cndmask_b32_e64 v140, v141, v140, s[36:37]
	v_mad_i64_i32 v[140:141], s[98:99], v140, s76, v[112:113]
	global_load_dwordx4 v[136:139], v[140:141], off
	s_waitcnt vmcnt(0)
	v_mov_b32_e32 v116, v66
	v_mov_b32_e32 v117, v66
	v_mov_b32_e32 v118, v67
	v_mov_b32_e32 v119, v67
	v_pk_mov_b32 v[120:121], v[66:67], v[66:67] op_sel:[1,0]
	s_mov_b32 s2, 8
	v_mov_b32_e32 v131, v124
	v_mov_b32_e32 v132, v128
	v_mov_b32_e32 v133, v126
	v_mov_b32_e32 v134, v109
	s_mov_b32 s5, s4
	s_mov_b32 s6, s4
	s_mov_b32 s7, s4
	s_mov_b32 s8, s4
	s_mov_b32 s9, s4
	s_mov_b32 s10, s4
	s_mov_b32 s11, s4
	s_mov_b32 s12, s4
	s_mov_b32 s13, s4
	s_mov_b32 s14, s4
	s_mov_b32 s15, s4
	s_mov_b32 s16, s4
	s_mov_b32 s17, s4
	s_mov_b32 s18, s4
	s_mov_b32 s19, s4
.LBB0_516:
	s_waitcnt vmcnt(2)
	s_add_i32 s2, s2, -1
	v_subrev_u32_e32 v132, 32, v132
	v_add_u32_e32 v131, 32, v131
	s_cmp_eq_u32 s2, 0
	v_mfma_f32_32x32x16_bf16 v[34:49], v[136:139], v[68:71], 0
	v_mfma_f32_32x32x16_bf16 v[50:65], v[136:139], v[72:75], 0
	v_mfma_f32_32x32x16_bf16 v[18:33], v[136:139], v[76:79], 0
	v_mfma_f32_32x32x16_bf16 v[2:17], v[136:139], v[80:83], 0
	s_cbranch_scc1 .Lssm516_nopf
	v_add_u32_e32 v140, s39, v131
	v_add_u32_e32 v141, s39, v132
	v_cndmask_b32_e64 v140, v141, v140, s[36:37]
	v_mad_i64_i32 v[140:141], s[98:99], v140, s76, v[112:113]
	global_load_dwordx4 v[136:139], v[140:141], off
.Lssm516_nopf:
	s_nop 15
	s_nop 9
	ds_write2_b32 v130, v34, v50 offset1:32
	ds_write2_b32 v130, v35, v51 offset0:128 offset1:160
	v_add_u32_e32 v34, 0x400, v130
	ds_write2_b32 v34, v36, v52 offset1:32
	ds_write2_b32 v34, v37, v53 offset0:128 offset1:160
	v_add_u32_e32 v35, 0x1000, v130
	v_add_u32_e32 v36, 0x1400, v130
	ds_write2_b32 v35, v38, v54 offset1:32
	ds_write2_b32 v35, v39, v55 offset0:128 offset1:160
	ds_write2_b32 v36, v40, v56 offset1:32
	ds_write2_b32 v36, v41, v57 offset0:128 offset1:160
	ds_write2_b32 v130, v18, v2 offset0:64 offset1:96
	ds_write2_b32 v130, v19, v3 offset0:192 offset1:224
	ds_write2_b32 v34, v20, v4 offset0:64 offset1:96
	ds_write2_b32 v34, v21, v5 offset0:192 offset1:224
	ds_write2_b32 v35, v22, v6 offset0:64 offset1:96
	ds_write2_b32 v35, v23, v7 offset0:192 offset1:224
	ds_write2_b32 v36, v24, v8 offset0:64 offset1:96
	ds_write2_b32 v36, v25, v9 offset0:192 offset1:224
	ds_read2st64_b32 v[2:3], v125 offset1:1
	v_pk_mul_f32 v[4:5], v[120:121], v[122:123] op_sel:[0,1]
	v_add_u32_e32 v37, 0x2800, v125
	v_pk_fma_f32 v[6:7], v[66:67], v[122:123], v[4:5] neg_lo:[0,0,1] neg_hi:[0,0,1]
	v_pk_fma_f32 v[4:5], v[66:67], v[122:123], v[4:5] op_sel_hi:[1,0,1]
	v_add_u32_e32 v38, 0x2c00, v125
	v_mov_b32_e32 v7, v5
	ds_read2st64_b32 v[4:5], v125 offset0:2 offset1:3
	s_waitcnt lgkmcnt(0)
	v_pk_add_f32 v[2:3], v[6:7], v[2:3]
	s_nop 0
	v_pk_mul_f32 v[6:7], v[120:121], v[2:3] op_sel:[0,1]
	v_cvt_pk_bf16_f32 v18, v2, v3
	v_pk_fma_f32 v[8:9], v[66:67], v[2:3], v[6:7] neg_lo:[0,0,1] neg_hi:[0,0,1]
	v_pk_fma_f32 v[2:3], v[66:67], v[2:3], v[6:7] op_sel_hi:[1,0,1]
	v_add_u32_e32 v6, 0x2000, v125
	v_mov_b32_e32 v9, v3
	v_pk_add_f32 v[2:3], v[4:5], v[8:9]
	s_nop 0
	v_cvt_pk_bf16_f32 v4, v2, v3
	ds_write2_b32 v6, v18, v4 offset1:68
	ds_read2st64_b32 v[4:5], v125 offset0:4 offset1:5
	v_pk_mul_f32 v[8:9], v[118:119], v[2:3]
	s_nop 0
	v_pk_fma_f32 v[18:19], v[116:117], v[2:3], v[8:9] op_sel:[0,0,1] op_sel_hi:[1,1,0] neg_lo:[0,0,1] neg_hi:[0,0,1]
	v_pk_fma_f32 v[2:3], v[116:117], v[2:3], v[8:9] op_sel:[0,0,1] op_sel_hi:[1,1,0]
	s_nop 0
	v_mov_b32_e32 v19, v3
	s_waitcnt lgkmcnt(0)
	v_pk_add_f32 v[2:3], v[4:5], v[18:19]
	ds_read2st64_b32 v[4:5], v125 offset0:6 offset1:7
	v_pk_mul_f32 v[8:9], v[118:119], v[2:3]
	v_cvt_pk_bf16_f32 v7, v2, v3
	v_pk_fma_f32 v[18:19], v[116:117], v[2:3], v[8:9] op_sel:[0,0,1] op_sel_hi:[1,1,0] neg_lo:[0,0,1] neg_hi:[0,0,1]
	v_pk_fma_f32 v[2:3], v[116:117], v[2:3], v[8:9] op_sel:[0,0,1] op_sel_hi:[1,1,0]
	s_nop 0
	v_mov_b32_e32 v19, v3
	s_waitcnt lgkmcnt(0)
	v_pk_add_f32 v[2:3], v[4:5], v[18:19]
	s_nop 0
	v_cvt_pk_bf16_f32 v4, v2, v3
	ds_write2_b32 v6, v7, v4 offset0:136 offset1:204
	ds_read2st64_b32 v[4:5], v125 offset0:8 offset1:9
	v_pk_mul_f32 v[8:9], v[118:119], v[2:3]
	v_add_u32_e32 v7, 0x2400, v125
	v_pk_fma_f32 v[18:19], v[116:117], v[2:3], v[8:9] op_sel:[0,0,1] op_sel_hi:[1,1,0] neg_lo:[0,0,1] neg_hi:[0,0,1]
	v_pk_fma_f32 v[2:3], v[116:117], v[2:3], v[8:9] op_sel:[0,0,1] op_sel_hi:[1,1,0]
	s_nop 0
	v_mov_b32_e32 v19, v3
	s_waitcnt lgkmcnt(0)
	v_pk_add_f32 v[2:3], v[4:5], v[18:19]
	ds_read2st64_b32 v[4:5], v125 offset0:10 offset1:11
	v_pk_mul_f32 v[8:9], v[118:119], v[2:3]
	v_cvt_pk_bf16_f32 v20, v2, v3
	v_pk_fma_f32 v[18:19], v[116:117], v[2:3], v[8:9] op_sel:[0,0,1] op_sel_hi:[1,1,0] neg_lo:[0,0,1] neg_hi:[0,0,1]
	v_pk_fma_f32 v[2:3], v[116:117], v[2:3], v[8:9] op_sel:[0,0,1] op_sel_hi:[1,1,0]
	s_nop 0
	v_mov_b32_e32 v19, v3
	s_waitcnt lgkmcnt(0)
	v_pk_add_f32 v[2:3], v[4:5], v[18:19]
	s_nop 0
	v_cvt_pk_bf16_f32 v4, v2, v3
	ds_write2_b32 v7, v20, v4 offset0:16 offset1:84
	ds_read2st64_b32 v[4:5], v125 offset0:12 offset1:13
	v_pk_mul_f32 v[8:9], v[118:119], v[2:3]
	s_nop 0
	v_pk_fma_f32 v[18:19], v[116:117], v[2:3], v[8:9] op_sel:[0,0,1] op_sel_hi:[1,1,0] neg_lo:[0,0,1] neg_hi:[0,0,1]
	v_pk_fma_f32 v[2:3], v[116:117], v[2:3], v[8:9] op_sel:[0,0,1] op_sel_hi:[1,1,0]
	s_nop 0
	v_mov_b32_e32 v19, v3
	s_waitcnt lgkmcnt(0)
	v_pk_add_f32 v[2:3], v[4:5], v[18:19]
	ds_read2st64_b32 v[4:5], v125 offset0:14 offset1:15
	v_pk_mul_f32 v[8:9], v[118:119], v[2:3]
	v_cvt_pk_bf16_f32 v20, v2, v3
	v_pk_fma_f32 v[18:19], v[116:117], v[2:3], v[8:9] op_sel:[0,0,1] op_sel_hi:[1,1,0] neg_lo:[0,0,1] neg_hi:[0,0,1]
	v_pk_fma_f32 v[2:3], v[116:117], v[2:3], v[8:9] op_sel:[0,0,1] op_sel_hi:[1,1,0]
	s_nop 0
	v_mov_b32_e32 v19, v3
	s_waitcnt lgkmcnt(0)
	v_pk_add_f32 v[2:3], v[4:5], v[18:19]
	s_nop 0
	v_cvt_pk_bf16_f32 v4, v2, v3
	ds_write2_b32 v7, v20, v4 offset0:152 offset1:220
	ds_read2st64_b32 v[4:5], v125 offset0:16 offset1:17
	v_pk_mul_f32 v[8:9], v[118:119], v[2:3]
	s_nop 0
	v_pk_fma_f32 v[18:19], v[116:117], v[2:3], v[8:9] op_sel:[0,0,1] op_sel_hi:[1,1,0] neg_lo:[0,0,1] neg_hi:[0,0,1]
	v_pk_fma_f32 v[2:3], v[116:117], v[2:3], v[8:9] op_sel:[0,0,1] op_sel_hi:[1,1,0]
	s_nop 0
	v_mov_b32_e32 v19, v3
	s_waitcnt lgkmcnt(0)
	v_pk_add_f32 v[2:3], v[4:5], v[18:19]
	ds_read2st64_b32 v[4:5], v125 offset0:18 offset1:19
	v_pk_mul_f32 v[8:9], v[118:119], v[2:3]
	v_cvt_pk_bf16_f32 v20, v2, v3
	v_pk_fma_f32 v[18:19], v[116:117], v[2:3], v[8:9] op_sel:[0,0,1] op_sel_hi:[1,1,0] neg_lo:[0,0,1] neg_hi:[0,0,1]
	v_pk_fma_f32 v[2:3], v[116:117], v[2:3], v[8:9] op_sel:[0,0,1] op_sel_hi:[1,1,0]
	s_nop 0
	v_mov_b32_e32 v19, v3
	s_waitcnt lgkmcnt(0)
	v_pk_add_f32 v[2:3], v[4:5], v[18:19]
	s_nop 0
	v_cvt_pk_bf16_f32 v4, v2, v3
	ds_write2_b32 v37, v20, v4 offset0:32 offset1:100
	ds_read2st64_b32 v[4:5], v125 offset0:20 offset1:21
	v_pk_mul_f32 v[8:9], v[118:119], v[2:3]
	s_nop 0
	v_pk_fma_f32 v[18:19], v[116:117], v[2:3], v[8:9] op_sel:[0,0,1] op_sel_hi:[1,1,0] neg_lo:[0,0,1] neg_hi:[0,0,1]
	v_pk_fma_f32 v[2:3], v[116:117], v[2:3], v[8:9] op_sel:[0,0,1] op_sel_hi:[1,1,0]
	s_nop 0
	v_mov_b32_e32 v19, v3
	s_waitcnt lgkmcnt(0)
	v_pk_add_f32 v[2:3], v[4:5], v[18:19]
	ds_read2st64_b32 v[4:5], v125 offset0:22 offset1:23
	v_pk_mul_f32 v[8:9], v[118:119], v[2:3]
	v_cvt_pk_bf16_f32 v20, v2, v3
	v_pk_fma_f32 v[18:19], v[116:117], v[2:3], v[8:9] op_sel:[0,0,1] op_sel_hi:[1,1,0] neg_lo:[0,0,1] neg_hi:[0,0,1]
	v_pk_fma_f32 v[2:3], v[116:117], v[2:3], v[8:9] op_sel:[0,0,1] op_sel_hi:[1,1,0]
	s_nop 0
	v_mov_b32_e32 v19, v3
	s_waitcnt lgkmcnt(0)
	v_pk_add_f32 v[2:3], v[4:5], v[18:19]
	s_nop 0
	v_cvt_pk_bf16_f32 v4, v2, v3
	ds_write2_b32 v37, v20, v4 offset0:168 offset1:236
	ds_read2st64_b32 v[4:5], v125 offset0:24 offset1:25
	v_pk_mul_f32 v[8:9], v[118:119], v[2:3]
	s_nop 0
	v_pk_fma_f32 v[18:19], v[116:117], v[2:3], v[8:9] op_sel:[0,0,1] op_sel_hi:[1,1,0] neg_lo:[0,0,1] neg_hi:[0,0,1]
	v_pk_fma_f32 v[2:3], v[116:117], v[2:3], v[8:9] op_sel:[0,0,1] op_sel_hi:[1,1,0]
	s_nop 0
	v_mov_b32_e32 v19, v3
	s_waitcnt lgkmcnt(0)
	v_pk_add_f32 v[2:3], v[4:5], v[18:19]
	ds_read2st64_b32 v[4:5], v125 offset0:26 offset1:27
	v_pk_mul_f32 v[8:9], v[118:119], v[2:3]
	v_cvt_pk_bf16_f32 v20, v2, v3
	v_pk_fma_f32 v[18:19], v[116:117], v[2:3], v[8:9] op_sel:[0,0,1] op_sel_hi:[1,1,0] neg_lo:[0,0,1] neg_hi:[0,0,1]
	v_pk_fma_f32 v[2:3], v[116:117], v[2:3], v[8:9] op_sel:[0,0,1] op_sel_hi:[1,1,0]
	s_nop 0
	v_mov_b32_e32 v19, v3
	s_waitcnt lgkmcnt(0)
	v_pk_add_f32 v[2:3], v[4:5], v[18:19]
	s_nop 0
	v_cvt_pk_bf16_f32 v4, v2, v3
	ds_write2_b32 v38, v20, v4 offset0:48 offset1:116
	ds_read2st64_b32 v[4:5], v125 offset0:28 offset1:29
	v_pk_mul_f32 v[8:9], v[118:119], v[2:3]
	s_nop 0
	v_pk_fma_f32 v[18:19], v[116:117], v[2:3], v[8:9] op_sel:[0,0,1] op_sel_hi:[1,1,0] neg_lo:[0,0,1] neg_hi:[0,0,1]
	v_pk_fma_f32 v[2:3], v[116:117], v[2:3], v[8:9] op_sel:[0,0,1] op_sel_hi:[1,1,0]
	s_nop 0
	v_mov_b32_e32 v19, v3
	s_waitcnt lgkmcnt(0)
	v_pk_add_f32 v[2:3], v[4:5], v[18:19]
	ds_read2st64_b32 v[4:5], v125 offset0:30 offset1:31
	v_pk_mul_f32 v[8:9], v[118:119], v[2:3]
	v_cvt_pk_bf16_f32 v20, v2, v3
	v_pk_fma_f32 v[18:19], v[116:117], v[2:3], v[8:9] op_sel:[0,0,1] op_sel_hi:[1,1,0] neg_lo:[0,0,1] neg_hi:[0,0,1]
	v_pk_fma_f32 v[2:3], v[116:117], v[2:3], v[8:9] op_sel:[0,0,1] op_sel_hi:[1,1,0]
	s_nop 0
	v_mov_b32_e32 v19, v3
	s_waitcnt lgkmcnt(0)
	v_pk_add_f32 v[8:9], v[4:5], v[18:19]
	s_nop 0
	v_cvt_pk_bf16_f32 v2, v8, v9
	ds_write2_b32 v38, v20, v2 offset0:184 offset1:252
	ds_read_b128 v[22:25], v127 offset:8192
	s_waitcnt lgkmcnt(0)
	v_mfma_f32_16x16x32_bf16 v[18:21], v[84:87], v[22:25], 0
	ds_read_b128 v[22:25], v127 offset:8256
	s_waitcnt lgkmcnt(0)
	v_mfma_f32_16x16x32_bf16 v[18:21], v[88:91], v[22:25], v[18:21]
	ds_read_b128 v[22:25], v127 offset:8320
	s_waitcnt lgkmcnt(0)
	v_mfma_f32_16x16x32_bf16 v[18:21], v[92:95], v[22:25], v[18:21]
	ds_read_b128 v[22:25], v127 offset:8384
	s_waitcnt lgkmcnt(0)
	v_mfma_f32_16x16x32_bf16 v[18:21], v[96:99], v[22:25], v[18:21]
	v_add_u32_e32 v25, s39, v134
	v_add_u32_e32 v24, s39, v133
	v_add_u32_e32 v22, 0xff, v25
	v_cndmask_b32_e64 v22, v22, v24, s[36:37]
	v_ashrrev_i32_e32 v23, 31, v22
	s_nop 2
	v_cvt_pk_bf16_f32 v18, v18, v19
	v_cvt_pk_bf16_f32 v19, v20, v21
	v_lshlrev_b64 v[20:21], 10, v[22:23]
	v_lshl_add_u64 v[20:21], v[114:115], 0, v[20:21]
	global_store_dwordx2 v[20:21], v[18:19], off
	ds_write2_b32 v130, v42, v58 offset1:32
	ds_write2_b32 v130, v43, v59 offset0:128 offset1:160
	ds_write2_b32 v34, v44, v60 offset1:32
	ds_write2_b32 v34, v45, v61 offset0:128 offset1:160
	ds_write2_b32 v35, v46, v62 offset1:32
	ds_write2_b32 v35, v47, v63 offset0:128 offset1:160
	ds_write2_b32 v36, v48, v64 offset1:32
	ds_write2_b32 v36, v49, v65 offset0:128 offset1:160
	ds_write2_b32 v130, v26, v10 offset0:64 offset1:96
	ds_write2_b32 v130, v27, v11 offset0:192 offset1:224
	ds_write2_b32 v34, v28, v12 offset0:64 offset1:96
	ds_write2_b32 v34, v29, v13 offset0:192 offset1:224
	ds_write2_b32 v35, v30, v14 offset0:64 offset1:96
	ds_write2_b32 v35, v31, v15 offset0:192 offset1:224
	ds_write2_b32 v36, v32, v16 offset0:64 offset1:96
	ds_write2_b32 v36, v33, v17 offset0:192 offset1:224
	ds_read2st64_b32 v[10:11], v125 offset1:1
	v_pk_mul_f32 v[12:13], v[118:119], v[8:9]
	v_pk_fma_f32 v[14:15], v[116:117], v[8:9], v[12:13] op_sel:[0,0,1] op_sel_hi:[1,1,0] neg_lo:[0,0,1] neg_hi:[0,0,1]
	v_pk_fma_f32 v[8:9], v[116:117], v[8:9], v[12:13] op_sel:[0,0,1] op_sel_hi:[1,1,0]
	v_subrev_u32_e32 v134, 32, v134
	v_mov_b32_e32 v15, v9
	s_waitcnt lgkmcnt(0)
	v_pk_add_f32 v[8:9], v[14:15], v[10:11]
	ds_read2st64_b32 v[10:11], v125 offset0:2 offset1:3
	v_pk_mul_f32 v[12:13], v[120:121], v[8:9] op_sel:[0,1]
	v_cvt_pk_bf16_f32 v16, v8, v9
	v_pk_fma_f32 v[14:15], v[66:67], v[8:9], v[12:13] neg_lo:[0,0,1] neg_hi:[0,0,1]
	v_pk_fma_f32 v[8:9], v[66:67], v[8:9], v[12:13] op_sel_hi:[1,0,1]
	v_add_u32_e32 v133, 32, v133
	v_mov_b32_e32 v15, v9
	s_waitcnt lgkmcnt(0)
	v_pk_add_f32 v[8:9], v[10:11], v[14:15]
	s_nop 0
	v_cvt_pk_bf16_f32 v10, v8, v9
	ds_write2_b32 v6, v16, v10 offset1:68
	ds_read2st64_b32 v[10:11], v125 offset0:4 offset1:5
	v_pk_mul_f32 v[12:13], v[118:119], v[8:9]
	s_nop 0
	v_pk_fma_f32 v[14:15], v[116:117], v[8:9], v[12:13] op_sel:[0,0,1] op_sel_hi:[1,1,0] neg_lo:[0,0,1] neg_hi:[0,0,1]
	v_pk_fma_f32 v[8:9], v[116:117], v[8:9], v[12:13] op_sel:[0,0,1] op_sel_hi:[1,1,0]
	s_nop 0
	v_mov_b32_e32 v15, v9
	s_waitcnt lgkmcnt(0)
	v_pk_add_f32 v[8:9], v[10:11], v[14:15]
	ds_read2st64_b32 v[10:11], v125 offset0:6 offset1:7
	v_pk_mul_f32 v[12:13], v[118:119], v[8:9]
	v_cvt_pk_bf16_f32 v16, v8, v9
	v_pk_fma_f32 v[14:15], v[116:117], v[8:9], v[12:13] op_sel:[0,0,1] op_sel_hi:[1,1,0] neg_lo:[0,0,1] neg_hi:[0,0,1]
	v_pk_fma_f32 v[8:9], v[116:117], v[8:9], v[12:13] op_sel:[0,0,1] op_sel_hi:[1,1,0]
	s_nop 0
	v_mov_b32_e32 v15, v9
	s_waitcnt lgkmcnt(0)
	v_pk_add_f32 v[8:9], v[10:11], v[14:15]
	s_nop 0
	v_cvt_pk_bf16_f32 v10, v8, v9
	ds_write2_b32 v6, v16, v10 offset0:136 offset1:204
	ds_read2st64_b32 v[10:11], v125 offset0:8 offset1:9
	v_pk_mul_f32 v[12:13], v[118:119], v[8:9]
	s_nop 0
	v_pk_fma_f32 v[14:15], v[116:117], v[8:9], v[12:13] op_sel:[0,0,1] op_sel_hi:[1,1,0] neg_lo:[0,0,1] neg_hi:[0,0,1]
	v_pk_fma_f32 v[8:9], v[116:117], v[8:9], v[12:13] op_sel:[0,0,1] op_sel_hi:[1,1,0]
	s_nop 0
	v_mov_b32_e32 v15, v9
	s_waitcnt lgkmcnt(0)
	v_pk_add_f32 v[8:9], v[10:11], v[14:15]
	ds_read2st64_b32 v[10:11], v125 offset0:10 offset1:11
	v_pk_mul_f32 v[12:13], v[118:119], v[8:9]
	v_cvt_pk_bf16_f32 v6, v8, v9
	v_pk_fma_f32 v[14:15], v[116:117], v[8:9], v[12:13] op_sel:[0,0,1] op_sel_hi:[1,1,0] neg_lo:[0,0,1] neg_hi:[0,0,1]
	v_pk_fma_f32 v[8:9], v[116:117], v[8:9], v[12:13] op_sel:[0,0,1] op_sel_hi:[1,1,0]
	s_nop 0
	v_mov_b32_e32 v15, v9
	s_waitcnt lgkmcnt(0)
	v_pk_add_f32 v[8:9], v[10:11], v[14:15]
	s_nop 0
	v_cvt_pk_bf16_f32 v10, v8, v9
	ds_write2_b32 v7, v6, v10 offset0:16 offset1:84
	ds_read2st64_b32 v[10:11], v125 offset0:12 offset1:13
	v_pk_mul_f32 v[12:13], v[118:119], v[8:9]
	s_nop 0
	v_pk_fma_f32 v[14:15], v[116:117], v[8:9], v[12:13] op_sel:[0,0,1] op_sel_hi:[1,1,0] neg_lo:[0,0,1] neg_hi:[0,0,1]
	v_pk_fma_f32 v[8:9], v[116:117], v[8:9], v[12:13] op_sel:[0,0,1] op_sel_hi:[1,1,0]
	s_nop 0
	v_mov_b32_e32 v15, v9
	s_waitcnt lgkmcnt(0)
	v_pk_add_f32 v[8:9], v[10:11], v[14:15]
	ds_read2st64_b32 v[10:11], v125 offset0:14 offset1:15
	v_pk_mul_f32 v[12:13], v[118:119], v[8:9]
	v_cvt_pk_bf16_f32 v6, v8, v9
	v_pk_fma_f32 v[14:15], v[116:117], v[8:9], v[12:13] op_sel:[0,0,1] op_sel_hi:[1,1,0] neg_lo:[0,0,1] neg_hi:[0,0,1]
	v_pk_fma_f32 v[8:9], v[116:117], v[8:9], v[12:13] op_sel:[0,0,1] op_sel_hi:[1,1,0]
	s_nop 0
	v_mov_b32_e32 v15, v9
	s_waitcnt lgkmcnt(0)
	v_pk_add_f32 v[8:9], v[10:11], v[14:15]
	s_nop 0
	v_cvt_pk_bf16_f32 v10, v8, v9
	ds_write2_b32 v7, v6, v10 offset0:152 offset1:220
	ds_read2st64_b32 v[6:7], v125 offset0:16 offset1:17
	v_pk_mul_f32 v[10:11], v[118:119], v[8:9]
	s_nop 0
	v_pk_fma_f32 v[12:13], v[116:117], v[8:9], v[10:11] op_sel:[0,0,1] op_sel_hi:[1,1,0] neg_lo:[0,0,1] neg_hi:[0,0,1]
	v_pk_fma_f32 v[8:9], v[116:117], v[8:9], v[10:11] op_sel:[0,0,1] op_sel_hi:[1,1,0]
	s_nop 0
	v_mov_b32_e32 v13, v9
	ds_read2st64_b32 v[8:9], v125 offset0:18 offset1:19
	s_waitcnt lgkmcnt(1)
	v_pk_add_f32 v[6:7], v[6:7], v[12:13]
	s_nop 0
	v_pk_mul_f32 v[10:11], v[118:119], v[6:7]
	v_cvt_pk_bf16_f32 v14, v6, v7
	v_pk_fma_f32 v[12:13], v[116:117], v[6:7], v[10:11] op_sel:[0,0,1] op_sel_hi:[1,1,0] neg_lo:[0,0,1] neg_hi:[0,0,1]
	v_pk_fma_f32 v[6:7], v[116:117], v[6:7], v[10:11] op_sel:[0,0,1] op_sel_hi:[1,1,0]
	s_nop 0
	v_mov_b32_e32 v13, v7
	s_waitcnt lgkmcnt(0)
	v_pk_add_f32 v[6:7], v[8:9], v[12:13]
	s_nop 0
	v_cvt_pk_bf16_f32 v8, v6, v7
	ds_write2_b32 v37, v14, v8 offset0:32 offset1:100
	ds_read2st64_b32 v[8:9], v125 offset0:20 offset1:21
	v_pk_mul_f32 v[10:11], v[118:119], v[6:7]
	s_nop 0
	v_pk_fma_f32 v[12:13], v[116:117], v[6:7], v[10:11] op_sel:[0,0,1] op_sel_hi:[1,1,0] neg_lo:[0,0,1] neg_hi:[0,0,1]
	v_pk_fma_f32 v[6:7], v[116:117], v[6:7], v[10:11] op_sel:[0,0,1] op_sel_hi:[1,1,0]
	s_nop 0
	v_mov_b32_e32 v13, v7
	s_waitcnt lgkmcnt(0)
	v_pk_add_f32 v[6:7], v[8:9], v[12:13]
	ds_read2st64_b32 v[8:9], v125 offset0:22 offset1:23
	v_pk_mul_f32 v[10:11], v[118:119], v[6:7]
	v_cvt_pk_bf16_f32 v14, v6, v7
	v_pk_fma_f32 v[12:13], v[116:117], v[6:7], v[10:11] op_sel:[0,0,1] op_sel_hi:[1,1,0] neg_lo:[0,0,1] neg_hi:[0,0,1]
	v_pk_fma_f32 v[6:7], v[116:117], v[6:7], v[10:11] op_sel:[0,0,1] op_sel_hi:[1,1,0]
	s_nop 0
	v_mov_b32_e32 v13, v7
	s_waitcnt lgkmcnt(0)
	v_pk_add_f32 v[6:7], v[8:9], v[12:13]
	s_nop 0
	v_cvt_pk_bf16_f32 v8, v6, v7
	ds_write2_b32 v37, v14, v8 offset0:168 offset1:236
	ds_read2st64_b32 v[8:9], v125 offset0:24 offset1:25
	v_pk_mul_f32 v[10:11], v[118:119], v[6:7]
	s_nop 0
	v_pk_fma_f32 v[12:13], v[116:117], v[6:7], v[10:11] op_sel:[0,0,1] op_sel_hi:[1,1,0] neg_lo:[0,0,1] neg_hi:[0,0,1]
	v_pk_fma_f32 v[6:7], v[116:117], v[6:7], v[10:11] op_sel:[0,0,1] op_sel_hi:[1,1,0]
	s_nop 0
	v_mov_b32_e32 v13, v7
	s_waitcnt lgkmcnt(0)
	v_pk_add_f32 v[6:7], v[8:9], v[12:13]
	ds_read2st64_b32 v[8:9], v125 offset0:26 offset1:27
	v_pk_mul_f32 v[10:11], v[118:119], v[6:7]
	v_cvt_pk_bf16_f32 v14, v6, v7
	v_pk_fma_f32 v[12:13], v[116:117], v[6:7], v[10:11] op_sel:[0,0,1] op_sel_hi:[1,1,0] neg_lo:[0,0,1] neg_hi:[0,0,1]
	v_pk_fma_f32 v[6:7], v[116:117], v[6:7], v[10:11] op_sel:[0,0,1] op_sel_hi:[1,1,0]
	s_nop 0
	v_mov_b32_e32 v13, v7
	s_waitcnt lgkmcnt(0)
	v_pk_add_f32 v[6:7], v[8:9], v[12:13]
	s_nop 0
	v_cvt_pk_bf16_f32 v8, v6, v7
	ds_write2_b32 v38, v14, v8 offset0:48 offset1:116
	ds_read2st64_b32 v[8:9], v125 offset0:28 offset1:29
	v_pk_mul_f32 v[10:11], v[118:119], v[6:7]
	s_nop 0
	v_pk_fma_f32 v[12:13], v[116:117], v[6:7], v[10:11] op_sel:[0,0,1] op_sel_hi:[1,1,0] neg_lo:[0,0,1] neg_hi:[0,0,1]
	v_pk_fma_f32 v[6:7], v[116:117], v[6:7], v[10:11] op_sel:[0,0,1] op_sel_hi:[1,1,0]
	s_nop 0
	v_mov_b32_e32 v13, v7
	s_waitcnt lgkmcnt(0)
	v_pk_add_f32 v[6:7], v[8:9], v[12:13]
	ds_read2st64_b32 v[8:9], v125 offset0:30 offset1:31
	v_pk_mul_f32 v[10:11], v[120:121], v[6:7] op_sel:[0,1]
	v_cvt_pk_bf16_f32 v14, v6, v7
	v_pk_fma_f32 v[12:13], v[66:67], v[6:7], v[10:11] neg_lo:[0,0,1] neg_hi:[0,0,1]
	v_pk_fma_f32 v[6:7], v[66:67], v[6:7], v[10:11] op_sel_hi:[1,0,1]
	s_nop 0
	v_mov_b32_e32 v13, v7
	s_waitcnt lgkmcnt(0)
	v_pk_add_f32 v[122:123], v[8:9], v[12:13]
	s_nop 0
	v_cvt_pk_bf16_f32 v6, v122, v123
	ds_write2_b32 v38, v14, v6 offset0:184 offset1:252
	ds_read_b128 v[6:9], v127 offset:8192
	s_waitcnt lgkmcnt(0)
	v_mfma_f32_16x16x32_bf16 v[2:5], v[84:87], v[6:9], 0
	ds_read_b128 v[6:9], v127 offset:8256
	s_waitcnt lgkmcnt(0)
	v_mfma_f32_16x16x32_bf16 v[2:5], v[88:91], v[6:9], v[2:5]
	ds_read_b128 v[6:9], v127 offset:8320
	s_waitcnt lgkmcnt(0)
	v_mfma_f32_16x16x32_bf16 v[2:5], v[92:95], v[6:9], v[2:5]
	ds_read_b128 v[6:9], v127 offset:8384
	s_waitcnt lgkmcnt(0)
	v_mfma_f32_16x16x32_bf16 v[2:5], v[96:99], v[6:9], v[2:5]
	v_add_u32_e32 v6, 16, v24
	v_add_u32_e32 v7, 0xef, v25
	v_cndmask_b32_e64 v6, v7, v6, s[36:37]
	v_ashrrev_i32_e32 v7, 31, v6
	s_nop 3
	v_cvt_pk_bf16_f32 v2, v2, v3
	v_cvt_pk_bf16_f32 v3, v4, v5
	v_lshlrev_b64 v[4:5], 10, v[6:7]
	v_lshl_add_u64 v[4:5], v[114:115], 0, v[4:5]
	global_store_dwordx2 v[4:5], v[2:3], off
	s_cbranch_scc0 .LBB0_516
	s_and_b64 vcc, exec, s[44:45]
	s_cbranch_vccz .LBB0_502
	s_ashr_i32 s39, s38, 31
	s_lshl_b64 s[2:3], s[38:39], 3
	s_add_u32 s2, s2, s0
	s_addc_u32 s3, s3, s1
	s_add_u32 s2, s2, s73
	s_addc_u32 s3, s3, s52
	s_lshl_b64 s[2:3], s[2:3], 14
	v_readlane_b32 s6, v251, 21
	v_readlane_b32 s7, v251, 22
	s_add_u32 s2, s6, s2
	v_lshl_or_b32 v2, s53, 9, v108
	s_addc_u32 s3, s7, s3
	global_store_dwordx2 v2, v[122:123], s[2:3]
	s_branch .LBB0_502

.LBB0_625:
	s_cmpk_gt_i32 s39, 0x7ff
	s_mov_b64 s[2:3], -1
	s_cbranch_scc0 .LBB0_629
	s_add_i32 s2, s39, 0xf800
	s_and_b32 s3, s2, 0xffff
	s_mulk_i32 s3, 0x2493
	s_lshr_b32 s3, s3, 16
	s_sub_i32 s5, s2, s3
	s_bfe_u32 s5, s5, 0xf0001
	s_add_i32 s5, s5, s3
	s_bfe_u32 s6, s5, 0xe0002
	s_mul_i32 s6, s6, 7
	s_bfe_u32 s37, s5, 0x10007
	s_and_b32 s3, s5, 0xffff
	s_sub_i32 s2, s2, s6
	s_bfe_u32 s36, s5, 0x80008
	s_lshl_b32 s5, s37, 5
	s_and_b32 s2, s2, 0xffff
	s_bfe_u32 s3, s3, 0x50002
	s_or_b32 s5, s5, s38
	s_or_b32 s6, s5, s3
	s_lshl_b32 s5, s2, 8
	s_xor_b32 s7, s5, 0x700
	s_cmp_eq_u32 s37, 0
	s_cselect_b64 vcc, -1, 0
	s_and_b64 s[8:9], vcc, exec
	s_cselect_b32 s5, s5, s7
	s_ashr_i32 s7, s6, 31
	s_lshl_b64 s[8:9], s[6:7], 10
	v_lshl_add_u64 v[2:3], v[98:99], 0, s[8:9]
	s_lshl_b64 s[6:7], s[6:7], 12
	v_lshl_add_u64 v[4:5], v[100:101], 0, s[6:7]
	global_load_dwordx2 v[82:83], v[2:3], off
	global_load_dwordx4 v[66:69], v[4:5], off
	global_load_dwordx4 v[70:73], v[4:5], off offset:1024
	global_load_dwordx4 v[74:77], v[4:5], off offset:2048
	global_load_dwordx4 v[78:81], v[4:5], off offset:3072
	s_lshl_b32 s8, s36, 11
	s_mov_b32 s7, s4
	v_mov_b32_e32 v106, 0
	s_lshl_b32 s6, s3, 5
	s_add_i32 s8, s8, s5
	s_mov_b32 s44, 0
	v_lshl_add_u64 v[84:85], v[102:103], 0, s[6:7]
	v_add_u32_e32 v88, s8, v125
	v_add_u32_e32 v89, s8, v126
	v_mov_b32_e32 v107, v106
	v_add_u32_e32 v140, s44, v89
	v_cndmask_b32_e32 v140, v88, v140, vcc
	v_mad_i64_i32 v[140:141], s[98:99], v140, s76, v[84:85]
	global_load_dwordx4 v[90:93], v[140:141], off
	s_waitcnt vmcnt(0)
	v_pk_mov_b32 v[86:87], v[82:83], v[82:83] op_sel:[1,0]
	s_mov_b32 s5, s4
	s_mov_b32 s6, s4
	s_mov_b32 s7, s4
	s_mov_b32 s8, s4
	s_mov_b32 s9, s4
	s_mov_b32 s10, s4
	s_mov_b32 s11, s4
	s_mov_b32 s12, s4
	s_mov_b32 s13, s4
	s_mov_b32 s14, s4
	s_mov_b32 s15, s4
	s_mov_b32 s16, s4
	s_mov_b32 s17, s4
	s_mov_b32 s18, s4
	s_mov_b32 s19, s4
.LBB0_627:
	s_waitcnt vmcnt(0)
	s_add_i32 s44, s44, 32
	v_subrev_u32_e32 v88, 32, v88
	s_cmpk_lg_i32 s44, 0x100
	v_mfma_f32_32x32x16_bf16 v[34:49], v[90:93], v[66:69], 0
	v_mfma_f32_32x32x16_bf16 v[50:65], v[90:93], v[70:73], 0
	v_mfma_f32_32x32x16_bf16 v[18:33], v[90:93], v[74:77], 0
	v_mfma_f32_32x32x16_bf16 v[2:17], v[90:93], v[78:81], 0
	s_cbranch_scc0 .Lssm627_nopf
	v_add_u32_e32 v140, s44, v89
	v_cndmask_b32_e32 v140, v88, v140, vcc
	v_mad_i64_i32 v[140:141], s[98:99], v140, s76, v[84:85]
	global_load_dwordx4 v[90:93], v[140:141], off
.Lssm627_nopf:
	s_nop 15
	s_nop 8
	ds_write_b32 v121, v34
	ds_write_b32 v121, v35 offset:512
	ds_write_b32 v121, v36 offset:1024
	ds_write_b32 v121, v37 offset:1536
	ds_write_b32 v121, v38 offset:4096
	ds_write_b32 v121, v39 offset:4608
	ds_write_b32 v121, v40 offset:5120
	ds_write_b32 v121, v41 offset:5632
	ds_write_b32 v121, v50 offset:128
	ds_write_b32 v121, v51 offset:640
	ds_write_b32 v121, v52 offset:1152
	ds_write_b32 v121, v53 offset:1664
	ds_write_b32 v121, v54 offset:4224
	ds_write_b32 v121, v55 offset:4736
	ds_write_b32 v121, v56 offset:5248
	ds_write_b32 v121, v57 offset:5760
	ds_write_b32 v121, v18 offset:256
	ds_write_b32 v121, v19 offset:768
	ds_write_b32 v121, v20 offset:1280
	ds_write_b32 v121, v21 offset:1792
	ds_write_b32 v121, v22 offset:4352
	ds_write_b32 v121, v23 offset:4864
	ds_write_b32 v121, v24 offset:5376
	ds_write_b32 v121, v25 offset:5888
	ds_write_b32 v121, v2 offset:384
	ds_write_b32 v121, v3 offset:896
	ds_write_b32 v121, v4 offset:1408
	ds_write_b32 v121, v5 offset:1920
	ds_write_b32 v121, v6 offset:4480
	ds_write_b32 v121, v7 offset:4992
	ds_write_b32 v121, v8 offset:5504
	ds_write_b32 v121, v9 offset:6016
	ds_read_b32 v4, v122
	ds_read_b32 v6, v122 offset:256
	v_pk_mul_f32 v[2:3], v[82:83], v[106:107]
	s_nop 0
	v_sub_f32_e32 v2, v2, v3
	s_waitcnt lgkmcnt(0)
	v_add_f32_e32 v2, v2, v4
	v_pk_mul_f32 v[4:5], v[86:87], v[106:107]
	s_nop 0
	v_add_f32_e32 v3, v4, v5
	v_add_f32_e32 v4, v3, v6
	ds_read_b32 v6, v122 offset:512
	ds_read_b32 v7, v122 offset:768
	ds_read_b32 v18, v122 offset:1024
	ds_read_b32 v19, v122 offset:1280
	v_pk_mul_f32 v[4:5], v[86:87], v[4:5] op_sel_hi:[1,0]
	s_nop 0
	v_pk_fma_f32 v[8:9], v[82:83], v[2:3], v[4:5] neg_lo:[0,0,1] neg_hi:[0,0,1]
	v_pk_fma_f32 v[2:3], v[82:83], v[2:3], v[4:5] op_sel_hi:[1,0,1]
	s_nop 0
	v_mov_b32_e32 v9, v3
	s_waitcnt lgkmcnt(2)
	v_pk_add_f32 v[2:3], v[6:7], v[8:9]
	s_nop 0
	v_pk_mul_f32 v[4:5], v[82:83], v[2:3]
	v_pk_mul_f32 v[2:3], v[82:83], v[2:3] op_sel:[0,1] op_sel_hi:[1,0]
	v_sub_f32_e32 v4, v4, v5
	v_add_f32_e32 v2, v2, v3
	s_waitcnt lgkmcnt(0)
	v_add_f32_e32 v2, v19, v2
	v_add_f32_e32 v4, v18, v4
	ds_read_b32 v6, v122 offset:1536
	ds_read_b32 v7, v122 offset:1792
	ds_read_b32 v18, v122 offset:2048
	ds_read_b32 v19, v122 offset:2304
	v_pk_mul_f32 v[2:3], v[86:87], v[2:3] op_sel_hi:[1,0]
	s_nop 0
	v_pk_fma_f32 v[8:9], v[82:83], v[4:5], v[2:3] neg_lo:[0,0,1] neg_hi:[0,0,1]
	v_pk_fma_f32 v[2:3], v[82:83], v[4:5], v[2:3] op_sel_hi:[1,0,1]
	s_nop 0
	v_mov_b32_e32 v9, v3
	s_waitcnt lgkmcnt(2)
	v_pk_add_f32 v[2:3], v[6:7], v[8:9]
	s_nop 0
	v_pk_mul_f32 v[4:5], v[82:83], v[2:3]
	v_pk_mul_f32 v[2:3], v[82:83], v[2:3] op_sel:[0,1] op_sel_hi:[1,0]
	v_sub_f32_e32 v4, v4, v5
	v_add_f32_e32 v2, v2, v3
	s_waitcnt lgkmcnt(0)
	v_add_f32_e32 v2, v19, v2
	v_add_f32_e32 v4, v18, v4
	ds_read_b32 v6, v122 offset:2560
	ds_read_b32 v7, v122 offset:2816
	ds_read_b32 v18, v122 offset:3072
	ds_read_b32 v19, v122 offset:3328
	v_pk_mul_f32 v[2:3], v[86:87], v[2:3] op_sel_hi:[1,0]
	s_nop 0
	v_pk_fma_f32 v[8:9], v[82:83], v[4:5], v[2:3] neg_lo:[0,0,1] neg_hi:[0,0,1]
	v_pk_fma_f32 v[2:3], v[82:83], v[4:5], v[2:3] op_sel_hi:[1,0,1]
	s_nop 0
	v_mov_b32_e32 v9, v3
	s_waitcnt lgkmcnt(2)
	v_pk_add_f32 v[2:3], v[6:7], v[8:9]
	s_nop 0
	v_pk_mul_f32 v[4:5], v[82:83], v[2:3]
	v_pk_mul_f32 v[2:3], v[82:83], v[2:3] op_sel:[0,1] op_sel_hi:[1,0]
	v_sub_f32_e32 v4, v4, v5
	v_add_f32_e32 v2, v2, v3
	s_waitcnt lgkmcnt(0)
	v_add_f32_e32 v2, v19, v2
	v_add_f32_e32 v4, v18, v4
	ds_read_b32 v6, v122 offset:3584
	ds_read_b32 v7, v122 offset:3840
	ds_read_b32 v18, v122 offset:4096
	ds_read_b32 v19, v122 offset:4352
	v_pk_mul_f32 v[2:3], v[86:87], v[2:3] op_sel_hi:[1,0]
	s_nop 0
	v_pk_fma_f32 v[8:9], v[82:83], v[4:5], v[2:3] neg_lo:[0,0,1] neg_hi:[0,0,1]
	v_pk_fma_f32 v[2:3], v[82:83], v[4:5], v[2:3] op_sel_hi:[1,0,1]
	s_nop 0
	v_mov_b32_e32 v9, v3
	s_waitcnt lgkmcnt(2)
	v_pk_add_f32 v[2:3], v[6:7], v[8:9]
	s_nop 0
	v_pk_mul_f32 v[4:5], v[82:83], v[2:3]
	v_pk_mul_f32 v[2:3], v[82:83], v[2:3] op_sel:[0,1] op_sel_hi:[1,0]
	v_sub_f32_e32 v4, v4, v5
	v_add_f32_e32 v2, v2, v3
	s_waitcnt lgkmcnt(0)
	v_add_f32_e32 v2, v19, v2
	v_add_f32_e32 v4, v18, v4
	ds_read_b32 v6, v122 offset:4608
	ds_read_b32 v7, v122 offset:4864
	ds_read_b32 v18, v122 offset:5120
	ds_read_b32 v19, v122 offset:5376
	v_pk_mul_f32 v[2:3], v[86:87], v[2:3] op_sel_hi:[1,0]
	s_nop 0
	v_pk_fma_f32 v[8:9], v[82:83], v[4:5], v[2:3] neg_lo:[0,0,1] neg_hi:[0,0,1]
	v_pk_fma_f32 v[2:3], v[82:83], v[4:5], v[2:3] op_sel_hi:[1,0,1]
	s_nop 0
	v_mov_b32_e32 v9, v3
	s_waitcnt lgkmcnt(2)
	v_pk_add_f32 v[2:3], v[6:7], v[8:9]
	s_nop 0
	v_pk_mul_f32 v[4:5], v[82:83], v[2:3]
	v_pk_mul_f32 v[2:3], v[82:83], v[2:3] op_sel:[0,1] op_sel_hi:[1,0]
	v_sub_f32_e32 v4, v4, v5
	v_add_f32_e32 v2, v2, v3
	s_waitcnt lgkmcnt(0)
	v_add_f32_e32 v2, v19, v2
	v_add_f32_e32 v4, v18, v4
	ds_read_b32 v6, v122 offset:5632
	ds_read_b32 v7, v122 offset:5888
	ds_read_b32 v18, v122 offset:6144
	ds_read_b32 v19, v122 offset:6400
	v_pk_mul_f32 v[2:3], v[86:87], v[2:3] op_sel_hi:[1,0]
	s_nop 0
	v_pk_fma_f32 v[8:9], v[82:83], v[4:5], v[2:3] neg_lo:[0,0,1] neg_hi:[0,0,1]
	v_pk_fma_f32 v[2:3], v[82:83], v[4:5], v[2:3] op_sel_hi:[1,0,1]
	s_nop 0
	v_mov_b32_e32 v9, v3
	s_waitcnt lgkmcnt(2)
	v_pk_add_f32 v[2:3], v[6:7], v[8:9]
	s_nop 0
	v_pk_mul_f32 v[4:5], v[82:83], v[2:3]
	v_pk_mul_f32 v[2:3], v[82:83], v[2:3] op_sel:[0,1] op_sel_hi:[1,0]
	v_sub_f32_e32 v4, v4, v5
	v_add_f32_e32 v2, v2, v3
	s_waitcnt lgkmcnt(0)
	v_add_f32_e32 v2, v19, v2
	v_add_f32_e32 v4, v18, v4
	ds_read_b32 v6, v122 offset:6656
	ds_read_b32 v7, v122 offset:6912
	ds_read_b32 v18, v122 offset:7168
	ds_read_b32 v19, v122 offset:7424
	v_pk_mul_f32 v[2:3], v[86:87], v[2:3] op_sel_hi:[1,0]
	s_nop 0
	v_pk_fma_f32 v[8:9], v[82:83], v[4:5], v[2:3] neg_lo:[0,0,1] neg_hi:[0,0,1]
	v_pk_fma_f32 v[2:3], v[82:83], v[4:5], v[2:3] op_sel_hi:[1,0,1]
	s_nop 0
	v_mov_b32_e32 v9, v3
	s_waitcnt lgkmcnt(2)
	v_pk_add_f32 v[2:3], v[6:7], v[8:9]
	ds_read_b32 v6, v122 offset:7680
	ds_read_b32 v7, v122 offset:7936
	v_pk_mul_f32 v[4:5], v[82:83], v[2:3]
	v_pk_mul_f32 v[2:3], v[82:83], v[2:3] op_sel:[0,1] op_sel_hi:[1,0]
	v_sub_f32_e32 v4, v4, v5
	v_add_f32_e32 v2, v2, v3
	s_waitcnt lgkmcnt(2)
	v_add_f32_e32 v2, v19, v2
	v_add_f32_e32 v4, v18, v4
	ds_write_b32 v121, v42
	ds_write_b32 v121, v43 offset:512
	ds_write_b32 v121, v44 offset:1024
	ds_write_b32 v121, v45 offset:1536
	ds_write_b32 v121, v46 offset:4096
	ds_write_b32 v121, v47 offset:4608
	ds_write_b32 v121, v48 offset:5120
	ds_write_b32 v121, v49 offset:5632
	ds_write_b32 v121, v58 offset:128
	ds_write_b32 v121, v59 offset:640
	ds_write_b32 v121, v60 offset:1152
	ds_write_b32 v121, v61 offset:1664
	ds_write_b32 v121, v62 offset:4224
	ds_write_b32 v121, v63 offset:4736
	ds_write_b32 v121, v64 offset:5248
	ds_write_b32 v121, v65 offset:5760
	ds_write_b32 v121, v26 offset:256
	ds_write_b32 v121, v27 offset:768
	ds_write_b32 v121, v28 offset:1280
	ds_write_b32 v121, v29 offset:1792
	ds_write_b32 v121, v30 offset:4352
	ds_write_b32 v121, v31 offset:4864
	ds_write_b32 v121, v32 offset:5376
	ds_write_b32 v121, v33 offset:5888
	ds_write_b32 v121, v10 offset:384
	ds_write_b32 v121, v11 offset:896
	ds_write_b32 v121, v12 offset:1408
	ds_write_b32 v121, v13 offset:1920
	ds_write_b32 v121, v14 offset:4480
	ds_write_b32 v121, v15 offset:4992
	ds_write_b32 v121, v16 offset:5504
	ds_write_b32 v121, v17 offset:6016
	v_pk_mul_f32 v[2:3], v[86:87], v[2:3] op_sel_hi:[1,0]
	ds_read_b32 v10, v122
	ds_read_b32 v11, v122 offset:256
	v_pk_fma_f32 v[8:9], v[82:83], v[4:5], v[2:3] neg_lo:[0,0,1] neg_hi:[0,0,1]
	v_pk_fma_f32 v[2:3], v[82:83], v[4:5], v[2:3] op_sel_hi:[1,0,1]
	s_nop 0
	v_mov_b32_e32 v9, v3
	s_waitcnt lgkmcnt(14)
	v_pk_add_f32 v[2:3], v[6:7], v[8:9]
	s_nop 0
	v_pk_mul_f32 v[4:5], v[82:83], v[2:3]
	v_pk_mul_f32 v[2:3], v[82:83], v[2:3] op_sel:[0,1] op_sel_hi:[1,0]
	v_sub_f32_e32 v4, v4, v5
	v_add_f32_e32 v2, v2, v3
	s_waitcnt lgkmcnt(0)
	v_add_f32_e32 v2, v2, v11
	v_add_f32_e32 v4, v4, v10
	ds_read_b32 v6, v122 offset:512
	ds_read_b32 v7, v122 offset:768
	ds_read_b32 v10, v122 offset:1024
	ds_read_b32 v11, v122 offset:1280
	v_pk_mul_f32 v[2:3], v[86:87], v[2:3] op_sel_hi:[1,0]
	s_nop 0
	v_pk_fma_f32 v[8:9], v[82:83], v[4:5], v[2:3] neg_lo:[0,0,1] neg_hi:[0,0,1]
	v_pk_fma_f32 v[2:3], v[82:83], v[4:5], v[2:3] op_sel_hi:[1,0,1]
	s_nop 0
	v_mov_b32_e32 v9, v3
	s_waitcnt lgkmcnt(2)
	v_pk_add_f32 v[2:3], v[6:7], v[8:9]
	s_nop 0
	v_pk_mul_f32 v[4:5], v[82:83], v[2:3]
	v_pk_mul_f32 v[2:3], v[82:83], v[2:3] op_sel:[0,1] op_sel_hi:[1,0]
	v_sub_f32_e32 v4, v4, v5
	v_add_f32_e32 v2, v2, v3
	s_waitcnt lgkmcnt(0)
	v_add_f32_e32 v2, v11, v2
	v_add_f32_e32 v4, v10, v4
	ds_read_b32 v6, v122 offset:1536
	ds_read_b32 v7, v122 offset:1792
	ds_read_b32 v10, v122 offset:2048
	ds_read_b32 v11, v122 offset:2304
	v_pk_mul_f32 v[2:3], v[86:87], v[2:3] op_sel_hi:[1,0]
	s_nop 0
	v_pk_fma_f32 v[8:9], v[82:83], v[4:5], v[2:3] neg_lo:[0,0,1] neg_hi:[0,0,1]
	v_pk_fma_f32 v[2:3], v[82:83], v[4:5], v[2:3] op_sel_hi:[1,0,1]
	s_nop 0
	v_mov_b32_e32 v9, v3
	s_waitcnt lgkmcnt(2)
	v_pk_add_f32 v[2:3], v[6:7], v[8:9]
	s_nop 0
	v_pk_mul_f32 v[4:5], v[82:83], v[2:3]
	v_pk_mul_f32 v[2:3], v[82:83], v[2:3] op_sel:[0,1] op_sel_hi:[1,0]
	v_sub_f32_e32 v4, v4, v5
	v_add_f32_e32 v2, v2, v3
	s_waitcnt lgkmcnt(0)
	v_add_f32_e32 v2, v11, v2
	v_add_f32_e32 v4, v10, v4
	ds_read_b32 v6, v122 offset:2560
	ds_read_b32 v7, v122 offset:2816
	ds_read_b32 v10, v122 offset:3072
	ds_read_b32 v11, v122 offset:3328
	v_pk_mul_f32 v[2:3], v[86:87], v[2:3] op_sel_hi:[1,0]
	s_nop 0
	v_pk_fma_f32 v[8:9], v[82:83], v[4:5], v[2:3] neg_lo:[0,0,1] neg_hi:[0,0,1]
	v_pk_fma_f32 v[2:3], v[82:83], v[4:5], v[2:3] op_sel_hi:[1,0,1]
	s_nop 0
	v_mov_b32_e32 v9, v3
	s_waitcnt lgkmcnt(2)
	v_pk_add_f32 v[2:3], v[6:7], v[8:9]
	s_nop 0
	v_pk_mul_f32 v[4:5], v[82:83], v[2:3]
	v_pk_mul_f32 v[2:3], v[82:83], v[2:3] op_sel:[0,1] op_sel_hi:[1,0]
	v_sub_f32_e32 v4, v4, v5
	v_add_f32_e32 v2, v2, v3
	s_waitcnt lgkmcnt(0)
	v_add_f32_e32 v2, v11, v2
	v_add_f32_e32 v4, v10, v4
	ds_read_b32 v6, v122 offset:3584
	ds_read_b32 v7, v122 offset:3840
	ds_read_b32 v10, v122 offset:4096
	ds_read_b32 v11, v122 offset:4352
	v_pk_mul_f32 v[2:3], v[86:87], v[2:3] op_sel_hi:[1,0]
	s_nop 0
	v_pk_fma_f32 v[8:9], v[82:83], v[4:5], v[2:3] neg_lo:[0,0,1] neg_hi:[0,0,1]
	v_pk_fma_f32 v[2:3], v[82:83], v[4:5], v[2:3] op_sel_hi:[1,0,1]
	s_nop 0
	v_mov_b32_e32 v9, v3
	s_waitcnt lgkmcnt(2)
	v_pk_add_f32 v[2:3], v[6:7], v[8:9]
	s_nop 0
	v_pk_mul_f32 v[4:5], v[82:83], v[2:3]
	v_pk_mul_f32 v[2:3], v[82:83], v[2:3] op_sel:[0,1] op_sel_hi:[1,0]
	v_sub_f32_e32 v4, v4, v5
	v_add_f32_e32 v2, v2, v3
	s_waitcnt lgkmcnt(0)
	v_add_f32_e32 v2, v11, v2
	v_add_f32_e32 v4, v10, v4
	ds_read_b32 v6, v122 offset:4608
	ds_read_b32 v7, v122 offset:4864
	ds_read_b32 v10, v122 offset:5120
	ds_read_b32 v11, v122 offset:5376
	v_pk_mul_f32 v[2:3], v[86:87], v[2:3] op_sel_hi:[1,0]
	s_nop 0
	v_pk_fma_f32 v[8:9], v[82:83], v[4:5], v[2:3] neg_lo:[0,0,1] neg_hi:[0,0,1]
	v_pk_fma_f32 v[2:3], v[82:83], v[4:5], v[2:3] op_sel_hi:[1,0,1]
	s_nop 0
	v_mov_b32_e32 v9, v3
	s_waitcnt lgkmcnt(2)
	v_pk_add_f32 v[2:3], v[6:7], v[8:9]
	s_nop 0
	v_pk_mul_f32 v[4:5], v[82:83], v[2:3]
	v_pk_mul_f32 v[2:3], v[82:83], v[2:3] op_sel:[0,1] op_sel_hi:[1,0]
	v_sub_f32_e32 v4, v4, v5
	v_add_f32_e32 v2, v2, v3
	s_waitcnt lgkmcnt(0)
	v_add_f32_e32 v2, v11, v2
	v_add_f32_e32 v4, v10, v4
	ds_read_b32 v6, v122 offset:5632
	ds_read_b32 v7, v122 offset:5888
	ds_read_b32 v10, v122 offset:6144
	ds_read_b32 v11, v122 offset:6400
	v_pk_mul_f32 v[2:3], v[86:87], v[2:3] op_sel_hi:[1,0]
	s_nop 0
	v_pk_fma_f32 v[8:9], v[82:83], v[4:5], v[2:3] neg_lo:[0,0,1] neg_hi:[0,0,1]
	v_pk_fma_f32 v[2:3], v[82:83], v[4:5], v[2:3] op_sel_hi:[1,0,1]
	s_nop 0
	v_mov_b32_e32 v9, v3
	s_waitcnt lgkmcnt(2)
	v_pk_add_f32 v[2:3], v[6:7], v[8:9]
	s_nop 0
	v_pk_mul_f32 v[4:5], v[82:83], v[2:3]
	v_pk_mul_f32 v[2:3], v[82:83], v[2:3] op_sel:[0,1] op_sel_hi:[1,0]
	v_sub_f32_e32 v4, v4, v5
	v_add_f32_e32 v2, v2, v3
	s_waitcnt lgkmcnt(0)
	v_add_f32_e32 v2, v11, v2
	v_add_f32_e32 v4, v10, v4
	ds_read_b32 v6, v122 offset:6656
	ds_read_b32 v7, v122 offset:6912
	ds_read_b32 v10, v122 offset:7168
	ds_read_b32 v11, v122 offset:7424
	v_pk_mul_f32 v[2:3], v[86:87], v[2:3] op_sel_hi:[1,0]
	s_nop 0
	v_pk_fma_f32 v[8:9], v[82:83], v[4:5], v[2:3] neg_lo:[0,0,1] neg_hi:[0,0,1]
	v_pk_fma_f32 v[2:3], v[82:83], v[4:5], v[2:3] op_sel_hi:[1,0,1]
	s_nop 0
	v_mov_b32_e32 v9, v3
	s_waitcnt lgkmcnt(2)
	v_pk_add_f32 v[2:3], v[6:7], v[8:9]
	ds_read_b32 v6, v122 offset:7680
	ds_read_b32 v7, v122 offset:7936
	v_pk_mul_f32 v[4:5], v[82:83], v[2:3]
	v_pk_mul_f32 v[2:3], v[82:83], v[2:3] op_sel:[0,1] op_sel_hi:[1,0]
	v_sub_f32_e32 v4, v4, v5
	v_add_f32_e32 v2, v2, v3
	s_waitcnt lgkmcnt(2)
	v_add_f32_e32 v2, v11, v2
	v_add_f32_e32 v4, v10, v4
	v_pk_mul_f32 v[2:3], v[86:87], v[2:3] op_sel_hi:[1,0]
	s_nop 0
	v_pk_fma_f32 v[8:9], v[82:83], v[4:5], v[2:3] neg_lo:[0,0,1] neg_hi:[0,0,1]
	v_pk_fma_f32 v[2:3], v[82:83], v[4:5], v[2:3] op_sel_hi:[1,0,1]
	s_nop 0
	v_mov_b32_e32 v9, v3
	s_waitcnt lgkmcnt(0)
	v_pk_add_f32 v[106:107], v[6:7], v[8:9]
	s_cbranch_scc1 .LBB0_627
	s_lshl_b32 s5, s36, 9
	s_lshl_b32 s6, s37, 8
	s_or_b32 s5, s5, s6
	s_lshl_b32 s3, s3, 3
	s_or_b32 s3, s5, s3
	s_add_i32 s3, s3, s2
	v_lshl_or_b32 v2, s3, 6, v204
	v_mov_b32_e32 v3, v1
	s_mov_b64 s[2:3], 0
.LBB0_629:
	s_and_b64 vcc, exec, s[2:3]
	v_readlane_b32 s2, v251, 19
	v_readlane_b32 s3, v251, 20
	s_cbranch_vccz .LBB0_624
	s_bfe_u32 s3, s39, 0x10005
	s_lshl_b32 s5, s3, 5
	s_and_b32 s2, s39, 31
	s_or_b32 s5, s5, s38
	s_ashr_i32 s36, s39, 6
	s_or_b32 s6, s5, s2
	s_cmp_eq_u32 s3, 0
	s_cselect_b64 vcc, -1, 0
	s_ashr_i32 s7, s6, 31
	s_lshl_b64 s[8:9], s[6:7], 10
	s_lshl_b64 s[6:7], s[6:7], 12
	v_lshl_add_u64 v[2:3], v[98:99], 0, s[8:9]
	v_lshl_add_u64 v[4:5], v[100:101], 0, s[6:7]
	global_load_dwordx2 v[108:109], v[2:3], off
	global_load_dwordx4 v[66:69], v[4:5], off
	global_load_dwordx4 v[70:73], v[4:5], off offset:1024
	global_load_dwordx4 v[74:77], v[4:5], off offset:2048
	v_lshl_add_u64 v[2:3], v[104:105], 0, s[6:7]
	global_load_dwordx4 v[78:81], v[4:5], off offset:3072
	global_load_dwordx4 v[82:85], v[2:3], off
	global_load_dwordx4 v[86:89], v[2:3], off offset:64
	global_load_dwordx4 v[90:93], v[2:3], off offset:128
	global_load_dwordx4 v[94:97], v[2:3], off offset:192
	s_mul_i32 s5, s3, 0xc00000
	s_lshl_b32 s44, s36, 8
	v_readlane_b32 s8, v251, 36
	v_readlane_b32 s9, v251, 37
	s_add_u32 s5, s8, s5
	s_mov_b32 s7, s4
	s_addc_u32 s8, s9, 0
	s_lshl_b32 s6, s2, 5
	v_lshl_add_u64 v[110:111], v[102:103], 0, s[6:7]
	s_add_u32 s6, s5, s6
	v_mov_b32_e32 v106, 0
	s_addc_u32 s7, s8, 0
	s_mov_b32 s37, 8
	v_mov_b32_e32 v129, v120
	v_mov_b32_e32 v130, v128
	v_mov_b32_e32 v131, v123
	v_mov_b32_e32 v132, v127
	v_lshl_add_u64 v[112:113], s[6:7], 0, v[0:1]
	v_mov_b32_e32 v107, v106
	v_add_u32_e32 v140, s44, v129
	v_add_u32_e32 v141, s44, v130
	v_cndmask_b32_e32 v140, v141, v140, vcc
	v_mad_i64_i32 v[140:141], s[98:99], v140, s76, v[110:111]
	global_load_dwordx4 v[134:137], v[140:141], off
	s_waitcnt vmcnt(0)
	v_mov_b32_e32 v114, v108
	v_mov_b32_e32 v115, v108
	v_mov_b32_e32 v116, v109
	v_mov_b32_e32 v117, v109
	v_pk_mov_b32 v[118:119], v[108:109], v[108:109] op_sel:[1,0]
	s_mov_b32 s5, s4
	s_mov_b32 s6, s4
	s_mov_b32 s7, s4
	s_mov_b32 s8, s4
	s_mov_b32 s9, s4
	s_mov_b32 s10, s4
	s_mov_b32 s11, s4
	s_mov_b32 s12, s4
	s_mov_b32 s13, s4
	s_mov_b32 s14, s4
	s_mov_b32 s15, s4
	s_mov_b32 s16, s4
	s_mov_b32 s17, s4
	s_mov_b32 s18, s4
	s_mov_b32 s19, s4
.LBB0_631:
	s_waitcnt vmcnt(2)
	s_add_i32 s37, s37, -1
	v_subrev_u32_e32 v130, 32, v130
	v_add_u32_e32 v129, 32, v129
	s_cmp_lg_u32 s37, 0
	v_mfma_f32_32x32x16_bf16 v[34:49], v[134:137], v[66:69], 0
	v_mfma_f32_32x32x16_bf16 v[50:65], v[134:137], v[70:73], 0
	v_mfma_f32_32x32x16_bf16 v[18:33], v[134:137], v[74:77], 0
	v_mfma_f32_32x32x16_bf16 v[2:17], v[134:137], v[78:81], 0
	s_cbranch_scc0 .Lssm631_nopf
	v_add_u32_e32 v140, s44, v129
	v_add_u32_e32 v141, s44, v130
	v_cndmask_b32_e32 v140, v141, v140, vcc
	v_mad_i64_i32 v[140:141], s[98:99], v140, s76, v[110:111]
	global_load_dwordx4 v[134:137], v[140:141], off
.Lssm631_nopf:
	s_nop 15
	s_nop 9
	ds_write2_b32 v121, v34, v50 offset1:32
	ds_write2_b32 v121, v35, v51 offset0:128 offset1:160
	v_add_u32_e32 v34, 0x400, v121
	ds_write2_b32 v34, v36, v52 offset1:32
	ds_write2_b32 v34, v37, v53 offset0:128 offset1:160
	v_add_u32_e32 v35, 0x1000, v121
	v_add_u32_e32 v36, 0x1400, v121
	ds_write2_b32 v35, v38, v54 offset1:32
	ds_write2_b32 v35, v39, v55 offset0:128 offset1:160
	ds_write2_b32 v36, v40, v56 offset1:32
	ds_write2_b32 v36, v41, v57 offset0:128 offset1:160
	ds_write2_b32 v121, v18, v2 offset0:64 offset1:96
	ds_write2_b32 v121, v19, v3 offset0:192 offset1:224
	ds_write2_b32 v34, v20, v4 offset0:64 offset1:96
	ds_write2_b32 v34, v21, v5 offset0:192 offset1:224
	ds_write2_b32 v35, v22, v6 offset0:64 offset1:96
	ds_write2_b32 v35, v23, v7 offset0:192 offset1:224
	ds_write2_b32 v36, v24, v8 offset0:64 offset1:96
	ds_write2_b32 v36, v25, v9 offset0:192 offset1:224
	ds_read2st64_b32 v[2:3], v122 offset1:1
	v_pk_mul_f32 v[4:5], v[118:119], v[106:107] op_sel:[0,1]
	v_add_u32_e32 v37, 0x2800, v122
	v_pk_fma_f32 v[6:7], v[108:109], v[106:107], v[4:5] neg_lo:[0,0,1] neg_hi:[0,0,1]
	v_pk_fma_f32 v[4:5], v[108:109], v[106:107], v[4:5] op_sel_hi:[1,0,1]
	v_add_u32_e32 v38, 0x2c00, v122
	v_mov_b32_e32 v7, v5
	ds_read2st64_b32 v[4:5], v122 offset0:2 offset1:3
	s_waitcnt lgkmcnt(0)
	v_pk_add_f32 v[2:3], v[6:7], v[2:3]
	s_nop 0
	v_pk_mul_f32 v[6:7], v[118:119], v[2:3] op_sel:[0,1]
	v_cvt_pk_bf16_f32 v18, v2, v3
	v_pk_fma_f32 v[8:9], v[108:109], v[2:3], v[6:7] neg_lo:[0,0,1] neg_hi:[0,0,1]
	v_pk_fma_f32 v[2:3], v[108:109], v[2:3], v[6:7] op_sel_hi:[1,0,1]
	v_add_u32_e32 v6, 0x2000, v122
	v_mov_b32_e32 v9, v3
	v_pk_add_f32 v[2:3], v[4:5], v[8:9]
	s_nop 0
	v_cvt_pk_bf16_f32 v4, v2, v3
	ds_write2_b32 v6, v18, v4 offset1:68
	ds_read2st64_b32 v[4:5], v122 offset0:4 offset1:5
	v_pk_mul_f32 v[8:9], v[116:117], v[2:3]
	s_nop 0
	v_pk_fma_f32 v[18:19], v[114:115], v[2:3], v[8:9] op_sel:[0,0,1] op_sel_hi:[1,1,0] neg_lo:[0,0,1] neg_hi:[0,0,1]
	v_pk_fma_f32 v[2:3], v[114:115], v[2:3], v[8:9] op_sel:[0,0,1] op_sel_hi:[1,1,0]
	s_nop 0
	v_mov_b32_e32 v19, v3
	s_waitcnt lgkmcnt(0)
	v_pk_add_f32 v[2:3], v[4:5], v[18:19]
	ds_read2st64_b32 v[4:5], v122 offset0:6 offset1:7
	v_pk_mul_f32 v[8:9], v[116:117], v[2:3]
	v_cvt_pk_bf16_f32 v7, v2, v3
	v_pk_fma_f32 v[18:19], v[114:115], v[2:3], v[8:9] op_sel:[0,0,1] op_sel_hi:[1,1,0] neg_lo:[0,0,1] neg_hi:[0,0,1]
	v_pk_fma_f32 v[2:3], v[114:115], v[2:3], v[8:9] op_sel:[0,0,1] op_sel_hi:[1,1,0]
	s_nop 0
	v_mov_b32_e32 v19, v3
	s_waitcnt lgkmcnt(0)
	v_pk_add_f32 v[2:3], v[4:5], v[18:19]
	s_nop 0
	v_cvt_pk_bf16_f32 v4, v2, v3
	ds_write2_b32 v6, v7, v4 offset0:136 offset1:204
	ds_read2st64_b32 v[4:5], v122 offset0:8 offset1:9
	v_pk_mul_f32 v[8:9], v[116:117], v[2:3]
	v_add_u32_e32 v7, 0x2400, v122
	v_pk_fma_f32 v[18:19], v[114:115], v[2:3], v[8:9] op_sel:[0,0,1] op_sel_hi:[1,1,0] neg_lo:[0,0,1] neg_hi:[0,0,1]
	v_pk_fma_f32 v[2:3], v[114:115], v[2:3], v[8:9] op_sel:[0,0,1] op_sel_hi:[1,1,0]
	s_nop 0
	v_mov_b32_e32 v19, v3
	s_waitcnt lgkmcnt(0)
	v_pk_add_f32 v[2:3], v[4:5], v[18:19]
	ds_read2st64_b32 v[4:5], v122 offset0:10 offset1:11
	v_pk_mul_f32 v[8:9], v[116:117], v[2:3]
	v_cvt_pk_bf16_f32 v20, v2, v3
	v_pk_fma_f32 v[18:19], v[114:115], v[2:3], v[8:9] op_sel:[0,0,1] op_sel_hi:[1,1,0] neg_lo:[0,0,1] neg_hi:[0,0,1]
	v_pk_fma_f32 v[2:3], v[114:115], v[2:3], v[8:9] op_sel:[0,0,1] op_sel_hi:[1,1,0]
	s_nop 0
	v_mov_b32_e32 v19, v3
	s_waitcnt lgkmcnt(0)
	v_pk_add_f32 v[2:3], v[4:5], v[18:19]
	s_nop 0
	v_cvt_pk_bf16_f32 v4, v2, v3
	ds_write2_b32 v7, v20, v4 offset0:16 offset1:84
	ds_read2st64_b32 v[4:5], v122 offset0:12 offset1:13
	v_pk_mul_f32 v[8:9], v[116:117], v[2:3]
	s_nop 0
	v_pk_fma_f32 v[18:19], v[114:115], v[2:3], v[8:9] op_sel:[0,0,1] op_sel_hi:[1,1,0] neg_lo:[0,0,1] neg_hi:[0,0,1]
	v_pk_fma_f32 v[2:3], v[114:115], v[2:3], v[8:9] op_sel:[0,0,1] op_sel_hi:[1,1,0]
	s_nop 0
	v_mov_b32_e32 v19, v3
	s_waitcnt lgkmcnt(0)
	v_pk_add_f32 v[2:3], v[4:5], v[18:19]
	ds_read2st64_b32 v[4:5], v122 offset0:14 offset1:15
	v_pk_mul_f32 v[8:9], v[116:117], v[2:3]
	v_cvt_pk_bf16_f32 v20, v2, v3
	v_pk_fma_f32 v[18:19], v[114:115], v[2:3], v[8:9] op_sel:[0,0,1] op_sel_hi:[1,1,0] neg_lo:[0,0,1] neg_hi:[0,0,1]
	v_pk_fma_f32 v[2:3], v[114:115], v[2:3], v[8:9] op_sel:[0,0,1] op_sel_hi:[1,1,0]
	s_nop 0
	v_mov_b32_e32 v19, v3
	s_waitcnt lgkmcnt(0)
	v_pk_add_f32 v[2:3], v[4:5], v[18:19]
	s_nop 0
	v_cvt_pk_bf16_f32 v4, v2, v3
	ds_write2_b32 v7, v20, v4 offset0:152 offset1:220
	ds_read2st64_b32 v[4:5], v122 offset0:16 offset1:17
	v_pk_mul_f32 v[8:9], v[116:117], v[2:3]
	s_nop 0
	v_pk_fma_f32 v[18:19], v[114:115], v[2:3], v[8:9] op_sel:[0,0,1] op_sel_hi:[1,1,0] neg_lo:[0,0,1] neg_hi:[0,0,1]
	v_pk_fma_f32 v[2:3], v[114:115], v[2:3], v[8:9] op_sel:[0,0,1] op_sel_hi:[1,1,0]
	s_nop 0
	v_mov_b32_e32 v19, v3
	s_waitcnt lgkmcnt(0)
	v_pk_add_f32 v[2:3], v[4:5], v[18:19]
	ds_read2st64_b32 v[4:5], v122 offset0:18 offset1:19
	v_pk_mul_f32 v[8:9], v[116:117], v[2:3]
	v_cvt_pk_bf16_f32 v20, v2, v3
	v_pk_fma_f32 v[18:19], v[114:115], v[2:3], v[8:9] op_sel:[0,0,1] op_sel_hi:[1,1,0] neg_lo:[0,0,1] neg_hi:[0,0,1]
	v_pk_fma_f32 v[2:3], v[114:115], v[2:3], v[8:9] op_sel:[0,0,1] op_sel_hi:[1,1,0]
	s_nop 0
	v_mov_b32_e32 v19, v3
	s_waitcnt lgkmcnt(0)
	v_pk_add_f32 v[2:3], v[4:5], v[18:19]
	s_nop 0
	v_cvt_pk_bf16_f32 v4, v2, v3
	ds_write2_b32 v37, v20, v4 offset0:32 offset1:100
	ds_read2st64_b32 v[4:5], v122 offset0:20 offset1:21
	v_pk_mul_f32 v[8:9], v[116:117], v[2:3]
	s_nop 0
	v_pk_fma_f32 v[18:19], v[114:115], v[2:3], v[8:9] op_sel:[0,0,1] op_sel_hi:[1,1,0] neg_lo:[0,0,1] neg_hi:[0,0,1]
	v_pk_fma_f32 v[2:3], v[114:115], v[2:3], v[8:9] op_sel:[0,0,1] op_sel_hi:[1,1,0]
	s_nop 0
	v_mov_b32_e32 v19, v3
	s_waitcnt lgkmcnt(0)
	v_pk_add_f32 v[2:3], v[4:5], v[18:19]
	ds_read2st64_b32 v[4:5], v122 offset0:22 offset1:23
	v_pk_mul_f32 v[8:9], v[116:117], v[2:3]
	v_cvt_pk_bf16_f32 v20, v2, v3
	v_pk_fma_f32 v[18:19], v[114:115], v[2:3], v[8:9] op_sel:[0,0,1] op_sel_hi:[1,1,0] neg_lo:[0,0,1] neg_hi:[0,0,1]
	v_pk_fma_f32 v[2:3], v[114:115], v[2:3], v[8:9] op_sel:[0,0,1] op_sel_hi:[1,1,0]
	s_nop 0
	v_mov_b32_e32 v19, v3
	s_waitcnt lgkmcnt(0)
	v_pk_add_f32 v[2:3], v[4:5], v[18:19]
	s_nop 0
	v_cvt_pk_bf16_f32 v4, v2, v3
	ds_write2_b32 v37, v20, v4 offset0:168 offset1:236
	ds_read2st64_b32 v[4:5], v122 offset0:24 offset1:25
	v_pk_mul_f32 v[8:9], v[116:117], v[2:3]
	s_nop 0
	v_pk_fma_f32 v[18:19], v[114:115], v[2:3], v[8:9] op_sel:[0,0,1] op_sel_hi:[1,1,0] neg_lo:[0,0,1] neg_hi:[0,0,1]
	v_pk_fma_f32 v[2:3], v[114:115], v[2:3], v[8:9] op_sel:[0,0,1] op_sel_hi:[1,1,0]
	s_nop 0
	v_mov_b32_e32 v19, v3
	s_waitcnt lgkmcnt(0)
	v_pk_add_f32 v[2:3], v[4:5], v[18:19]
	ds_read2st64_b32 v[4:5], v122 offset0:26 offset1:27
	v_pk_mul_f32 v[8:9], v[116:117], v[2:3]
	v_cvt_pk_bf16_f32 v20, v2, v3
	v_pk_fma_f32 v[18:19], v[114:115], v[2:3], v[8:9] op_sel:[0,0,1] op_sel_hi:[1,1,0] neg_lo:[0,0,1] neg_hi:[0,0,1]
	v_pk_fma_f32 v[2:3], v[114:115], v[2:3], v[8:9] op_sel:[0,0,1] op_sel_hi:[1,1,0]
	s_nop 0
	v_mov_b32_e32 v19, v3
	s_waitcnt lgkmcnt(0)
	v_pk_add_f32 v[2:3], v[4:5], v[18:19]
	s_nop 0
	v_cvt_pk_bf16_f32 v4, v2, v3
	ds_write2_b32 v38, v20, v4 offset0:48 offset1:116
	ds_read2st64_b32 v[4:5], v122 offset0:28 offset1:29
	v_pk_mul_f32 v[8:9], v[116:117], v[2:3]
	s_nop 0
	v_pk_fma_f32 v[18:19], v[114:115], v[2:3], v[8:9] op_sel:[0,0,1] op_sel_hi:[1,1,0] neg_lo:[0,0,1] neg_hi:[0,0,1]
	v_pk_fma_f32 v[2:3], v[114:115], v[2:3], v[8:9] op_sel:[0,0,1] op_sel_hi:[1,1,0]
	s_nop 0
	v_mov_b32_e32 v19, v3
	s_waitcnt lgkmcnt(0)
	v_pk_add_f32 v[2:3], v[4:5], v[18:19]
	ds_read2st64_b32 v[4:5], v122 offset0:30 offset1:31
	v_pk_mul_f32 v[8:9], v[116:117], v[2:3]
	v_cvt_pk_bf16_f32 v20, v2, v3
	v_pk_fma_f32 v[18:19], v[114:115], v[2:3], v[8:9] op_sel:[0,0,1] op_sel_hi:[1,1,0] neg_lo:[0,0,1] neg_hi:[0,0,1]
	v_pk_fma_f32 v[2:3], v[114:115], v[2:3], v[8:9] op_sel:[0,0,1] op_sel_hi:[1,1,0]
	s_nop 0
	v_mov_b32_e32 v19, v3
	s_waitcnt lgkmcnt(0)
	v_pk_add_f32 v[8:9], v[4:5], v[18:19]
	s_nop 0
	v_cvt_pk_bf16_f32 v2, v8, v9
	ds_write2_b32 v38, v20, v2 offset0:184 offset1:252
	ds_read_b128 v[22:25], v124 offset:8192
	s_waitcnt lgkmcnt(0)
	v_mfma_f32_16x16x32_bf16 v[18:21], v[82:85], v[22:25], 0
	ds_read_b128 v[22:25], v124 offset:8256
	s_waitcnt lgkmcnt(0)
	v_mfma_f32_16x16x32_bf16 v[18:21], v[86:89], v[22:25], v[18:21]
	ds_read_b128 v[22:25], v124 offset:8320
	s_waitcnt lgkmcnt(0)
	v_mfma_f32_16x16x32_bf16 v[18:21], v[90:93], v[22:25], v[18:21]
	ds_read_b128 v[22:25], v124 offset:8384
	s_waitcnt lgkmcnt(0)
	v_mfma_f32_16x16x32_bf16 v[18:21], v[94:97], v[22:25], v[18:21]
	v_add_u32_e32 v25, s44, v132
	v_add_u32_e32 v24, s44, v131
	v_add_u32_e32 v22, 0xff, v25
	v_cndmask_b32_e32 v22, v22, v24, vcc
	v_ashrrev_i32_e32 v23, 31, v22
	s_nop 2
	v_cvt_pk_bf16_f32 v18, v18, v19
	v_cvt_pk_bf16_f32 v19, v20, v21
	v_lshlrev_b64 v[20:21], 10, v[22:23]
	v_lshl_add_u64 v[20:21], v[112:113], 0, v[20:21]
	global_store_dwordx2 v[20:21], v[18:19], off
	ds_write2_b32 v121, v42, v58 offset1:32
	ds_write2_b32 v121, v43, v59 offset0:128 offset1:160
	ds_write2_b32 v34, v44, v60 offset1:32
	ds_write2_b32 v34, v45, v61 offset0:128 offset1:160
	ds_write2_b32 v35, v46, v62 offset1:32
	ds_write2_b32 v35, v47, v63 offset0:128 offset1:160
	ds_write2_b32 v36, v48, v64 offset1:32
	ds_write2_b32 v36, v49, v65 offset0:128 offset1:160
	ds_write2_b32 v121, v26, v10 offset0:64 offset1:96
	ds_write2_b32 v121, v27, v11 offset0:192 offset1:224
	ds_write2_b32 v34, v28, v12 offset0:64 offset1:96
	ds_write2_b32 v34, v29, v13 offset0:192 offset1:224
	ds_write2_b32 v35, v30, v14 offset0:64 offset1:96
	ds_write2_b32 v35, v31, v15 offset0:192 offset1:224
	ds_write2_b32 v36, v32, v16 offset0:64 offset1:96
	ds_write2_b32 v36, v33, v17 offset0:192 offset1:224
	ds_read2st64_b32 v[10:11], v122 offset1:1
	v_pk_mul_f32 v[12:13], v[116:117], v[8:9]
	v_pk_fma_f32 v[14:15], v[114:115], v[8:9], v[12:13] op_sel:[0,0,1] op_sel_hi:[1,1,0] neg_lo:[0,0,1] neg_hi:[0,0,1]
	v_pk_fma_f32 v[8:9], v[114:115], v[8:9], v[12:13] op_sel:[0,0,1] op_sel_hi:[1,1,0]
	v_subrev_u32_e32 v132, 32, v132
	v_mov_b32_e32 v15, v9
	s_waitcnt lgkmcnt(0)
	v_pk_add_f32 v[8:9], v[14:15], v[10:11]
	ds_read2st64_b32 v[10:11], v122 offset0:2 offset1:3
	v_pk_mul_f32 v[12:13], v[118:119], v[8:9] op_sel:[0,1]
	v_cvt_pk_bf16_f32 v16, v8, v9
	v_pk_fma_f32 v[14:15], v[108:109], v[8:9], v[12:13] neg_lo:[0,0,1] neg_hi:[0,0,1]
	v_pk_fma_f32 v[8:9], v[108:109], v[8:9], v[12:13] op_sel_hi:[1,0,1]
	v_add_u32_e32 v131, 32, v131
	v_mov_b32_e32 v15, v9
	s_waitcnt lgkmcnt(0)
	v_pk_add_f32 v[8:9], v[10:11], v[14:15]
	s_nop 0
	v_cvt_pk_bf16_f32 v10, v8, v9
	ds_write2_b32 v6, v16, v10 offset1:68
	ds_read2st64_b32 v[10:11], v122 offset0:4 offset1:5
	v_pk_mul_f32 v[12:13], v[116:117], v[8:9]
	s_nop 0
	v_pk_fma_f32 v[14:15], v[114:115], v[8:9], v[12:13] op_sel:[0,0,1] op_sel_hi:[1,1,0] neg_lo:[0,0,1] neg_hi:[0,0,1]
	v_pk_fma_f32 v[8:9], v[114:115], v[8:9], v[12:13] op_sel:[0,0,1] op_sel_hi:[1,1,0]
	s_nop 0
	v_mov_b32_e32 v15, v9
	s_waitcnt lgkmcnt(0)
	v_pk_add_f32 v[8:9], v[10:11], v[14:15]
	ds_read2st64_b32 v[10:11], v122 offset0:6 offset1:7
	v_pk_mul_f32 v[12:13], v[116:117], v[8:9]
	v_cvt_pk_bf16_f32 v16, v8, v9
	v_pk_fma_f32 v[14:15], v[114:115], v[8:9], v[12:13] op_sel:[0,0,1] op_sel_hi:[1,1,0] neg_lo:[0,0,1] neg_hi:[0,0,1]
	v_pk_fma_f32 v[8:9], v[114:115], v[8:9], v[12:13] op_sel:[0,0,1] op_sel_hi:[1,1,0]
	s_nop 0
	v_mov_b32_e32 v15, v9
	s_waitcnt lgkmcnt(0)
	v_pk_add_f32 v[8:9], v[10:11], v[14:15]
	s_nop 0
	v_cvt_pk_bf16_f32 v10, v8, v9
	ds_write2_b32 v6, v16, v10 offset0:136 offset1:204
	ds_read2st64_b32 v[10:11], v122 offset0:8 offset1:9
	v_pk_mul_f32 v[12:13], v[116:117], v[8:9]
	s_nop 0
	v_pk_fma_f32 v[14:15], v[114:115], v[8:9], v[12:13] op_sel:[0,0,1] op_sel_hi:[1,1,0] neg_lo:[0,0,1] neg_hi:[0,0,1]
	v_pk_fma_f32 v[8:9], v[114:115], v[8:9], v[12:13] op_sel:[0,0,1] op_sel_hi:[1,1,0]
	s_nop 0
	v_mov_b32_e32 v15, v9
	s_waitcnt lgkmcnt(0)
	v_pk_add_f32 v[8:9], v[10:11], v[14:15]
	ds_read2st64_b32 v[10:11], v122 offset0:10 offset1:11
	v_pk_mul_f32 v[12:13], v[116:117], v[8:9]
	v_cvt_pk_bf16_f32 v6, v8, v9
	v_pk_fma_f32 v[14:15], v[114:115], v[8:9], v[12:13] op_sel:[0,0,1] op_sel_hi:[1,1,0] neg_lo:[0,0,1] neg_hi:[0,0,1]
	v_pk_fma_f32 v[8:9], v[114:115], v[8:9], v[12:13] op_sel:[0,0,1] op_sel_hi:[1,1,0]
	s_nop 0
	v_mov_b32_e32 v15, v9
	s_waitcnt lgkmcnt(0)
	v_pk_add_f32 v[8:9], v[10:11], v[14:15]
	s_nop 0
	v_cvt_pk_bf16_f32 v10, v8, v9
	ds_write2_b32 v7, v6, v10 offset0:16 offset1:84
	ds_read2st64_b32 v[10:11], v122 offset0:12 offset1:13
	v_pk_mul_f32 v[12:13], v[116:117], v[8:9]
	s_nop 0
	v_pk_fma_f32 v[14:15], v[114:115], v[8:9], v[12:13] op_sel:[0,0,1] op_sel_hi:[1,1,0] neg_lo:[0,0,1] neg_hi:[0,0,1]
	v_pk_fma_f32 v[8:9], v[114:115], v[8:9], v[12:13] op_sel:[0,0,1] op_sel_hi:[1,1,0]
	s_nop 0
	v_mov_b32_e32 v15, v9
	s_waitcnt lgkmcnt(0)
	v_pk_add_f32 v[8:9], v[10:11], v[14:15]
	ds_read2st64_b32 v[10:11], v122 offset0:14 offset1:15
	v_pk_mul_f32 v[12:13], v[116:117], v[8:9]
	v_cvt_pk_bf16_f32 v6, v8, v9
	v_pk_fma_f32 v[14:15], v[114:115], v[8:9], v[12:13] op_sel:[0,0,1] op_sel_hi:[1,1,0] neg_lo:[0,0,1] neg_hi:[0,0,1]
	v_pk_fma_f32 v[8:9], v[114:115], v[8:9], v[12:13] op_sel:[0,0,1] op_sel_hi:[1,1,0]
	s_nop 0
	v_mov_b32_e32 v15, v9
	s_waitcnt lgkmcnt(0)
	v_pk_add_f32 v[8:9], v[10:11], v[14:15]
	s_nop 0
	v_cvt_pk_bf16_f32 v10, v8, v9
	ds_write2_b32 v7, v6, v10 offset0:152 offset1:220
	ds_read2st64_b32 v[6:7], v122 offset0:16 offset1:17
	v_pk_mul_f32 v[10:11], v[116:117], v[8:9]
	s_nop 0
	v_pk_fma_f32 v[12:13], v[114:115], v[8:9], v[10:11] op_sel:[0,0,1] op_sel_hi:[1,1,0] neg_lo:[0,0,1] neg_hi:[0,0,1]
	v_pk_fma_f32 v[8:9], v[114:115], v[8:9], v[10:11] op_sel:[0,0,1] op_sel_hi:[1,1,0]
	s_nop 0
	v_mov_b32_e32 v13, v9
	ds_read2st64_b32 v[8:9], v122 offset0:18 offset1:19
	s_waitcnt lgkmcnt(1)
	v_pk_add_f32 v[6:7], v[6:7], v[12:13]
	s_nop 0
	v_pk_mul_f32 v[10:11], v[116:117], v[6:7]
	v_cvt_pk_bf16_f32 v14, v6, v7
	v_pk_fma_f32 v[12:13], v[114:115], v[6:7], v[10:11] op_sel:[0,0,1] op_sel_hi:[1,1,0] neg_lo:[0,0,1] neg_hi:[0,0,1]
	v_pk_fma_f32 v[6:7], v[114:115], v[6:7], v[10:11] op_sel:[0,0,1] op_sel_hi:[1,1,0]
	s_nop 0
	v_mov_b32_e32 v13, v7
	s_waitcnt lgkmcnt(0)
	v_pk_add_f32 v[6:7], v[8:9], v[12:13]
	s_nop 0
	v_cvt_pk_bf16_f32 v8, v6, v7
	ds_write2_b32 v37, v14, v8 offset0:32 offset1:100
	ds_read2st64_b32 v[8:9], v122 offset0:20 offset1:21
	v_pk_mul_f32 v[10:11], v[116:117], v[6:7]
	s_nop 0
	v_pk_fma_f32 v[12:13], v[114:115], v[6:7], v[10:11] op_sel:[0,0,1] op_sel_hi:[1,1,0] neg_lo:[0,0,1] neg_hi:[0,0,1]
	v_pk_fma_f32 v[6:7], v[114:115], v[6:7], v[10:11] op_sel:[0,0,1] op_sel_hi:[1,1,0]
	s_nop 0
	v_mov_b32_e32 v13, v7
	s_waitcnt lgkmcnt(0)
	v_pk_add_f32 v[6:7], v[8:9], v[12:13]
	ds_read2st64_b32 v[8:9], v122 offset0:22 offset1:23
	v_pk_mul_f32 v[10:11], v[116:117], v[6:7]
	v_cvt_pk_bf16_f32 v14, v6, v7
	v_pk_fma_f32 v[12:13], v[114:115], v[6:7], v[10:11] op_sel:[0,0,1] op_sel_hi:[1,1,0] neg_lo:[0,0,1] neg_hi:[0,0,1]
	v_pk_fma_f32 v[6:7], v[114:115], v[6:7], v[10:11] op_sel:[0,0,1] op_sel_hi:[1,1,0]
	s_nop 0
	v_mov_b32_e32 v13, v7
	s_waitcnt lgkmcnt(0)
	v_pk_add_f32 v[6:7], v[8:9], v[12:13]
	s_nop 0
	v_cvt_pk_bf16_f32 v8, v6, v7
	ds_write2_b32 v37, v14, v8 offset0:168 offset1:236
	ds_read2st64_b32 v[8:9], v122 offset0:24 offset1:25
	v_pk_mul_f32 v[10:11], v[116:117], v[6:7]
	s_nop 0
	v_pk_fma_f32 v[12:13], v[114:115], v[6:7], v[10:11] op_sel:[0,0,1] op_sel_hi:[1,1,0] neg_lo:[0,0,1] neg_hi:[0,0,1]
	v_pk_fma_f32 v[6:7], v[114:115], v[6:7], v[10:11] op_sel:[0,0,1] op_sel_hi:[1,1,0]
	s_nop 0
	v_mov_b32_e32 v13, v7
	s_waitcnt lgkmcnt(0)
	v_pk_add_f32 v[6:7], v[8:9], v[12:13]
	ds_read2st64_b32 v[8:9], v122 offset0:26 offset1:27
	v_pk_mul_f32 v[10:11], v[116:117], v[6:7]
	v_cvt_pk_bf16_f32 v14, v6, v7
	v_pk_fma_f32 v[12:13], v[114:115], v[6:7], v[10:11] op_sel:[0,0,1] op_sel_hi:[1,1,0] neg_lo:[0,0,1] neg_hi:[0,0,1]
	v_pk_fma_f32 v[6:7], v[114:115], v[6:7], v[10:11] op_sel:[0,0,1] op_sel_hi:[1,1,0]
	s_nop 0
	v_mov_b32_e32 v13, v7
	s_waitcnt lgkmcnt(0)
	v_pk_add_f32 v[6:7], v[8:9], v[12:13]
	s_nop 0
	v_cvt_pk_bf16_f32 v8, v6, v7
	ds_write2_b32 v38, v14, v8 offset0:48 offset1:116
	ds_read2st64_b32 v[8:9], v122 offset0:28 offset1:29
	v_pk_mul_f32 v[10:11], v[116:117], v[6:7]
	s_nop 0
	v_pk_fma_f32 v[12:13], v[114:115], v[6:7], v[10:11] op_sel:[0,0,1] op_sel_hi:[1,1,0] neg_lo:[0,0,1] neg_hi:[0,0,1]
	v_pk_fma_f32 v[6:7], v[114:115], v[6:7], v[10:11] op_sel:[0,0,1] op_sel_hi:[1,1,0]
	s_nop 0
	v_mov_b32_e32 v13, v7
	s_waitcnt lgkmcnt(0)
	v_pk_add_f32 v[6:7], v[8:9], v[12:13]
	ds_read2st64_b32 v[8:9], v122 offset0:30 offset1:31
	v_pk_mul_f32 v[10:11], v[118:119], v[6:7] op_sel:[0,1]
	v_cvt_pk_bf16_f32 v14, v6, v7
	v_pk_fma_f32 v[12:13], v[108:109], v[6:7], v[10:11] neg_lo:[0,0,1] neg_hi:[0,0,1]
	v_pk_fma_f32 v[6:7], v[108:109], v[6:7], v[10:11] op_sel_hi:[1,0,1]
	s_nop 0
	v_mov_b32_e32 v13, v7
	s_waitcnt lgkmcnt(0)
	v_pk_add_f32 v[106:107], v[8:9], v[12:13]
	s_nop 0
	v_cvt_pk_bf16_f32 v6, v106, v107
	ds_write2_b32 v38, v14, v6 offset0:184 offset1:252
	ds_read_b128 v[6:9], v124 offset:8192
	s_waitcnt lgkmcnt(0)
	v_mfma_f32_16x16x32_bf16 v[2:5], v[82:85], v[6:9], 0
	ds_read_b128 v[6:9], v124 offset:8256
	s_waitcnt lgkmcnt(0)
	v_mfma_f32_16x16x32_bf16 v[2:5], v[86:89], v[6:9], v[2:5]
	ds_read_b128 v[6:9], v124 offset:8320
	s_waitcnt lgkmcnt(0)
	v_mfma_f32_16x16x32_bf16 v[2:5], v[90:93], v[6:9], v[2:5]
	ds_read_b128 v[6:9], v124 offset:8384
	s_waitcnt lgkmcnt(0)
	v_mfma_f32_16x16x32_bf16 v[2:5], v[94:97], v[6:9], v[2:5]
	v_add_u32_e32 v6, 16, v24
	v_add_u32_e32 v7, 0xef, v25
	v_cndmask_b32_e32 v6, v7, v6, vcc
	v_ashrrev_i32_e32 v7, 31, v6
	s_nop 3
	v_cvt_pk_bf16_f32 v2, v2, v3
	v_cvt_pk_bf16_f32 v3, v4, v5
	v_lshlrev_b64 v[4:5], 10, v[6:7]
	v_lshl_add_u64 v[4:5], v[112:113], 0, v[4:5]
	global_store_dwordx2 v[4:5], v[2:3], off
	s_cbranch_scc1 .LBB0_631
	s_ashr_i32 s37, s36, 31
	s_lshl_b64 s[6:7], s[36:37], 3
	s_add_u32 s5, s6, s0
	s_addc_u32 s7, s7, s1
	s_or_b32 s6, s5, s3
	s_lshl_b64 s[6:7], s[6:7], 11
	s_lshl_b32 s2, s2, 6
	s_or_b32 s2, s6, s2
	v_or_b32_e32 v2, s2, v204
	v_readlane_b32 s2, v251, 21
	v_mov_b32_e32 v3, s7
	v_readlane_b32 s3, v251, 22
	s_branch .LBB0_624
